# GEMM mainloops: DMA staging moved into MMA segments (vmcnt 6/2), no pre-barrier lgkmcnt, closing barrier hoisted 8 MFMAs with prio-2 tail
# speedup vs baseline: 1.0725x; 1.0725x over previous
; #define PG8_STAGE(bufoff, gbase, voff) do { _Pragma("unroll") for (int _i = 0; _i < 2; ++_i) \
;         __builtin_amdgcn_global_load_lds((const unsigned*)((const char*)(gbase) + (voff)[_i]), (PG8_LAS unsigned*)(lds + (bufoff) + ldsw + _i * 8192), 16, 0, 0); } while (0)
; #define PG8_LDA(dst, b, h) do { _Pragma("unroll") for (int m = 0; m < 4; ++m) _Pragma("unroll") for (int k = 0; k < 2; ++k) dst[m][k] = *(const PG8_LAS bf16x8*)(lds + PG8_SA(b, h) + aoff + m * 2048 + k * 1024); } while (0)
; #define PG8_LDB(dst, b, h) do { _Pragma("unroll") for (int n = 0; n < 2; ++n) _Pragma("unroll") for (int k = 0; k < 2; ++k) dst[n][k] = *(const PG8_LAS bf16x8*)(lds + PG8_SB(b, h) + boff + n * 2048 + k * 1024); } while (0)
; #define PG8_MMA(ai, bj, At, Bt) do { __builtin_amdgcn_s_setprio(1); _Pragma("unroll") for (int m = 0; m < 4; ++m) _Pragma("unroll") for (int n = 0; n < 2; ++n) _Pragma("unroll") for (int k = 0; k < 2; ++k) \
;         acc[ai][bj][m][n] = __builtin_amdgcn_mfma_f32_16x16x32_bf16(Bt[n][k], At[m][k], acc[ai][bj][m][n], 0, 0, 0); __builtin_amdgcn_s_setprio(0); } while (0)
; #define PG8_WAIT_V(n) asm volatile("s_waitcnt vmcnt(" #n ")" ::: "memory")
; #define PG8_WAIT_L(n) asm volatile("s_waitcnt lgkmcnt(" #n ")" ::: "memory")
; #define PG8_BAR __builtin_amdgcn_s_barrier()
; #define PG8_SCHED __builtin_amdgcn_sched_barrier(0)
; template <class Epi, class Sched, bool ALIGN_EPI = false, bool SP2 = false>
; __device__ __forceinline__ void gemm_phase(PG8_LAS unsigned char* lds, const Gemm g, const Sched& S, const Epi& E) {
;     ...
;             const char* a2 = last ? nA : cA + (size_t)(t + 2) * kstep; const char* b2 = last ? nB : cB + (size_t)(t + 2) * kstep;
;             const char* a3 = a2 + kstep; const char* b3 = b2 + kstep;
;             if (last && has_next) S.a_ready(nxt);
;             if constexpr (SP2) {
;             PG8_LDB(B0, 0, 0); PG8_LDB(B1, 0, 1); PG8_SCHED; PG8_LDA(At, 0, 0); PG8_STAGE(PG8_SA(1, 1), a1 + hstep, voffA);
;             PG8_WAIT_V(8); PG8_WAIT_L(0); PG8_BAR; PG8_MMA(0, 0, At, B0); PG8_MMA(0, 1, At, B1); PG8_BAR; PG8_SCHED;
;             PG8_LDA(At, 0, 1); PG8_STAGE(PG8_SB(0, 0), b2, voffB); PG8_STAGE(PG8_SB(0, 1), b2 + hstep, voffB); PG8_STAGE(PG8_SA(0, 0), a2, voffA);
;             PG8_WAIT_V(8); PG8_WAIT_L(0); PG8_BAR; PG8_MMA(1, 0, At, B0); PG8_MMA(1, 1, At, B1); PG8_BAR; PG8_SCHED;
.LBB0_138:
	s_add_u32 s20, s88, 0xfff80080
	s_addc_u32 s21, s89, -1
	s_add_i32 s29, 0, 0x10000
	s_cmp_eq_u32 s28, 28
	s_cselect_b32 s91, s78, s21
	s_cselect_b32 s90, s79, s20
	v_add_u32_e32 v155, s29, v149
	s_cselect_b32 s21, s45, s92
	s_cselect_b32 s20, s81, s83
	s_add_i32 s46, 0, 0x14000
	ds_read_b128 v[144:147], v155
	ds_read_b128 v[156:159], v155 offset:1024
	ds_read_b128 v[174:177], v155 offset:2048
	ds_read_b128 v[178:181], v155 offset:3072
	v_add_u32_e32 v155, s46, v149
	ds_read_b128 v[182:185], v155
	ds_read_b128 v[186:189], v155 offset:1024
	ds_read_b128 v[206:209], v155 offset:2048
	ds_read_b128 v[210:213], v155 offset:3072
	v_lshl_add_u64 v[246:247], s[88:89], 0, v[140:141]
	s_add_i32 m0, s30, 0xc000
	ds_read_b128 v[214:217], v154
	ds_read_b128 v[218:221], v154 offset:1024
	ds_read_b128 v[222:225], v154 offset:2048
	ds_read_b128 v[226:229], v154 offset:3072
	ds_read_b128 v[230:233], v154 offset:4096
	ds_read_b128 v[234:237], v154 offset:5120
	ds_read_b128 v[238:241], v154 offset:6144
	ds_read_b128 v[242:245], v154 offset:7168
	s_waitcnt vmcnt(6)
	s_nop 0
	s_barrier
	s_setprio 1
	s_waitcnt lgkmcnt(0)
	v_mfma_f32_16x16x32_bf16 v[124:127], v[144:147], v[214:217], v[124:127]
	global_load_lds_dwordx4 v[246:247], off
	v_mfma_f32_16x16x32_bf16 v[120:123], v[174:177], v[214:217], v[120:123]
	v_lshl_add_u64 v[246:247], s[88:89], 0, v[142:143]
	v_mfma_f32_16x16x32_bf16 v[108:111], v[144:147], v[222:225], v[108:111]
	s_add_i32 m0, s30, 0xe000
	v_mfma_f32_16x16x32_bf16 v[104:107], v[174:177], v[222:225], v[104:107]
	global_load_lds_dwordx4 v[246:247], off
	v_mfma_f32_16x16x32_bf16 v[92:95], v[144:147], v[230:233], v[92:95]
	v_mfma_f32_16x16x32_bf16 v[88:91], v[174:177], v[230:233], v[88:91]
	v_mfma_f32_16x16x32_bf16 v[76:79], v[144:147], v[238:241], v[76:79]
	v_mfma_f32_16x16x32_bf16 v[72:75], v[174:177], v[238:241], v[72:75]
	v_mfma_f32_16x16x32_bf16 v[124:127], v[156:159], v[218:221], v[124:127]
	v_mfma_f32_16x16x32_bf16 v[120:123], v[178:181], v[218:221], v[120:123]
	v_mfma_f32_16x16x32_bf16 v[108:111], v[156:159], v[226:229], v[108:111]
	v_mfma_f32_16x16x32_bf16 v[104:107], v[178:181], v[226:229], v[104:107]
	v_mfma_f32_16x16x32_bf16 v[92:95], v[156:159], v[234:237], v[92:95]
	v_mfma_f32_16x16x32_bf16 v[88:91], v[178:181], v[234:237], v[88:91]
	v_mfma_f32_16x16x32_bf16 v[76:79], v[156:159], v[242:245], v[76:79]
	v_mfma_f32_16x16x32_bf16 v[72:75], v[178:181], v[242:245], v[72:75]
	s_setprio 0
	s_setprio 1
	v_mfma_f32_16x16x32_bf16 v[116:119], v[182:185], v[214:217], v[116:119]
	v_mfma_f32_16x16x32_bf16 v[112:115], v[206:209], v[214:217], v[112:115]
	v_mfma_f32_16x16x32_bf16 v[100:103], v[182:185], v[222:225], v[100:103]
	v_mfma_f32_16x16x32_bf16 v[96:99], v[206:209], v[222:225], v[96:99]
	v_mfma_f32_16x16x32_bf16 v[84:87], v[182:185], v[230:233], v[84:87]
	v_mfma_f32_16x16x32_bf16 v[80:83], v[206:209], v[230:233], v[80:83]
	v_mfma_f32_16x16x32_bf16 v[68:71], v[182:185], v[238:241], v[68:71]
	v_mfma_f32_16x16x32_bf16 v[64:67], v[206:209], v[238:241], v[64:67]
	s_barrier
	s_setprio 2
	v_mfma_f32_16x16x32_bf16 v[116:119], v[186:189], v[218:221], v[116:119]
	v_mfma_f32_16x16x32_bf16 v[112:115], v[210:213], v[218:221], v[112:115]
	v_mfma_f32_16x16x32_bf16 v[100:103], v[186:189], v[226:229], v[100:103]
	v_mfma_f32_16x16x32_bf16 v[96:99], v[210:213], v[226:229], v[96:99]
	v_mfma_f32_16x16x32_bf16 v[84:87], v[186:189], v[234:237], v[84:87]
	v_mfma_f32_16x16x32_bf16 v[80:83], v[210:213], v[234:237], v[80:83]
	v_mfma_f32_16x16x32_bf16 v[68:71], v[186:189], v[242:245], v[68:71]
	v_mfma_f32_16x16x32_bf16 v[64:67], v[210:213], v[242:245], v[64:67]
	s_setprio 0
	s_add_i32 s29, s29, s25
	v_lshl_add_u64 v[246:247], s[20:21], 0, v[132:133]
	s_mov_b32 m0, s29
	ds_read_b128 v[214:217], v154 offset:16384
	ds_read_b128 v[218:221], v154 offset:17408
	ds_read_b128 v[222:225], v154 offset:18432
	ds_read_b128 v[226:229], v154 offset:19456
	ds_read_b128 v[230:233], v154 offset:20480
	ds_read_b128 v[234:237], v154 offset:21504
	ds_read_b128 v[238:241], v154 offset:22528
	ds_read_b128 v[242:245], v154 offset:23552
	s_waitcnt vmcnt(2)
	s_nop 0
	s_barrier
	s_setprio 1
	s_waitcnt lgkmcnt(0)
	v_mfma_f32_16x16x32_bf16 v[60:63], v[144:147], v[214:217], v[60:63]
	global_load_lds_dwordx4 v[246:247], off
	v_mfma_f32_16x16x32_bf16 v[56:59], v[174:177], v[214:217], v[56:59]
	s_add_i32 m0, s29, 0x2000
	v_mfma_f32_16x16x32_bf16 v[44:47], v[144:147], v[222:225], v[44:47]
	s_add_u32 s94, s20, 0x80000
	v_mfma_f32_16x16x32_bf16 v[40:43], v[174:177], v[222:225], v[40:43]
	v_lshl_add_u64 v[248:249], s[20:21], 0, v[128:129]
	v_mfma_f32_16x16x32_bf16 v[28:31], v[144:147], v[230:233], v[28:31]
	s_addc_u32 s95, s21, 0
	v_mfma_f32_16x16x32_bf16 v[24:27], v[174:177], v[230:233], v[24:27]
	s_add_i32 s29, s46, s25
	v_mfma_f32_16x16x32_bf16 v[12:15], v[144:147], v[238:241], v[12:15]
	global_load_lds_dwordx4 v[248:249], off
	v_mfma_f32_16x16x32_bf16 v[8:11], v[174:177], v[238:241], v[8:11]
	v_lshl_add_u64 v[250:251], s[94:95], 0, v[132:133]
	v_mfma_f32_16x16x32_bf16 v[60:63], v[156:159], v[218:221], v[60:63]
	s_mov_b32 m0, s29
	v_mfma_f32_16x16x32_bf16 v[56:59], v[178:181], v[218:221], v[56:59]
	v_lshl_add_u64 v[196:197], s[90:91], 0, v[130:131]
	v_mfma_f32_16x16x32_bf16 v[44:47], v[156:159], v[226:229], v[44:47]
	global_load_lds_dwordx4 v[250:251], off
	v_mfma_f32_16x16x32_bf16 v[40:43], v[178:181], v[226:229], v[40:43]
	v_lshl_add_u64 v[250:251], s[94:95], 0, v[128:129]
	v_mfma_f32_16x16x32_bf16 v[28:31], v[156:159], v[234:237], v[28:31]
	s_add_i32 m0, s29, 0x2000
	v_mfma_f32_16x16x32_bf16 v[24:27], v[178:181], v[234:237], v[24:27]
	global_load_lds_dwordx4 v[250:251], off
	v_mfma_f32_16x16x32_bf16 v[12:15], v[156:159], v[242:245], v[12:15]
	v_lshl_add_u64 v[250:251], s[90:91], 0, v[134:135]
	v_mfma_f32_16x16x32_bf16 v[8:11], v[178:181], v[242:245], v[8:11]
	s_mov_b32 m0, s30
	s_setprio 0
	s_setprio 1
	v_mfma_f32_16x16x32_bf16 v[52:55], v[182:185], v[214:217], v[52:55]
	global_load_lds_dwordx4 v[250:251], off
	v_mfma_f32_16x16x32_bf16 v[48:51], v[206:209], v[214:217], v[48:51]
	s_mov_b32 m0, s31
	v_mfma_f32_16x16x32_bf16 v[36:39], v[182:185], v[222:225], v[36:39]
	global_load_lds_dwordx4 v[196:197], off
	v_mfma_f32_16x16x32_bf16 v[32:35], v[206:209], v[222:225], v[32:35]
	v_mfma_f32_16x16x32_bf16 v[20:23], v[182:185], v[230:233], v[20:23]
	v_mfma_f32_16x16x32_bf16 v[16:19], v[206:209], v[230:233], v[16:19]
	v_mfma_f32_16x16x32_bf16 v[4:7], v[182:185], v[238:241], v[4:7]
	v_mfma_f32_16x16x32_bf16 v[0:3], v[206:209], v[238:241], v[0:3]
	s_barrier
; #define PG8_STAGE(bufoff, gbase, voff) do { _Pragma("unroll") for (int _i = 0; _i < 2; ++_i) \
;         __builtin_amdgcn_global_load_lds((const unsigned*)((const char*)(gbase) + (voff)[_i]), (PG8_LAS unsigned*)(lds + (bufoff) + ldsw + _i * 8192), 16, 0, 0); } while (0)
; #define PG8_LDA(dst, b, h) do { _Pragma("unroll") for (int m = 0; m < 4; ++m) _Pragma("unroll") for (int k = 0; k < 2; ++k) dst[m][k] = *(const PG8_LAS bf16x8*)(lds + PG8_SA(b, h) + aoff + m * 2048 + k * 1024); } while (0)
; #define PG8_LDB(dst, b, h) do { _Pragma("unroll") for (int n = 0; n < 2; ++n) _Pragma("unroll") for (int k = 0; k < 2; ++k) dst[n][k] = *(const PG8_LAS bf16x8*)(lds + PG8_SB(b, h) + boff + n * 2048 + k * 1024); } while (0)
; #define PG8_MMA(ai, bj, At, Bt) do { __builtin_amdgcn_s_setprio(1); _Pragma("unroll") for (int m = 0; m < 4; ++m) _Pragma("unroll") for (int n = 0; n < 2; ++n) _Pragma("unroll") for (int k = 0; k < 2; ++k) \
;         acc[ai][bj][m][n] = __builtin_amdgcn_mfma_f32_16x16x32_bf16(Bt[n][k], At[m][k], acc[ai][bj][m][n], 0, 0, 0); __builtin_amdgcn_s_setprio(0); } while (0)
; #define PG8_WAIT_V(n) asm volatile("s_waitcnt vmcnt(" #n ")" ::: "memory")
; #define PG8_WAIT_L(n) asm volatile("s_waitcnt lgkmcnt(" #n ")" ::: "memory")
; #define PG8_BAR __builtin_amdgcn_s_barrier()
; #define PG8_SCHED __builtin_amdgcn_sched_barrier(0)
; template <class Epi, class Sched, bool ALIGN_EPI = false, bool SP2 = false>
; __device__ __forceinline__ void gemm_phase(PG8_LAS unsigned char* lds, const Gemm g, const Sched& S, const Epi& E) {
;     ...
;             PG8_WAIT_V(8); PG8_WAIT_L(0); PG8_BAR; PG8_MMA(1, 0, At, B0); PG8_MMA(1, 1, At, B1); PG8_BAR; PG8_SCHED;
;             PG8_LDB(B0, 1, 0); PG8_LDB(B1, 1, 1); PG8_SCHED; PG8_LDA(At, 1, 0); PG8_STAGE(PG8_SA(0, 1), a2 + hstep, voffA);
;             PG8_WAIT_V(8); PG8_WAIT_L(0); PG8_BAR; PG8_MMA(0, 0, At, B0); PG8_MMA(0, 1, At, B1); PG8_BAR; PG8_SCHED;
	s_setprio 2
	v_mfma_f32_16x16x32_bf16 v[52:55], v[186:189], v[218:221], v[52:55]
	v_mfma_f32_16x16x32_bf16 v[48:51], v[210:213], v[218:221], v[48:51]
	v_mfma_f32_16x16x32_bf16 v[36:39], v[186:189], v[226:229], v[36:39]
	v_mfma_f32_16x16x32_bf16 v[32:35], v[210:213], v[226:229], v[32:35]
	v_mfma_f32_16x16x32_bf16 v[20:23], v[186:189], v[234:237], v[20:23]
	v_mfma_f32_16x16x32_bf16 v[16:19], v[210:213], v[234:237], v[16:19]
	v_mfma_f32_16x16x32_bf16 v[4:7], v[186:189], v[242:245], v[4:7]
	v_mfma_f32_16x16x32_bf16 v[0:3], v[210:213], v[242:245], v[0:3]
	s_setprio 0
	s_add_i32 s29, 0, 0x18000
	v_add_u32_e32 v155, s29, v149
	s_add_i32 s46, 0, 0x1c000
	ds_read_b128 v[144:147], v155
	ds_read_b128 v[156:159], v155 offset:1024
	ds_read_b128 v[174:177], v155 offset:2048
	ds_read_b128 v[178:181], v155 offset:3072
	v_add_u32_e32 v155, s46, v149
	ds_read_b128 v[182:185], v155
	ds_read_b128 v[186:189], v155 offset:1024
	ds_read_b128 v[206:209], v155 offset:2048
	ds_read_b128 v[210:213], v155 offset:3072
	s_add_u32 s90, s90, 0x80000
	s_addc_u32 s91, s91, 0
	s_mov_b32 m0, s70
	v_lshl_add_u64 v[198:199], s[90:91], 0, v[134:135]
	ds_read_b128 v[214:217], v154 offset:32768
	ds_read_b128 v[218:221], v154 offset:33792
	ds_read_b128 v[222:225], v154 offset:34816
	ds_read_b128 v[226:229], v154 offset:35840
	ds_read_b128 v[230:233], v154 offset:36864
	ds_read_b128 v[234:237], v154 offset:37888
	ds_read_b128 v[238:241], v154 offset:38912
	ds_read_b128 v[242:245], v154 offset:39936
	s_waitcnt vmcnt(6)
	s_nop 0
	s_barrier
	s_setprio 1
	s_waitcnt lgkmcnt(0)
	v_mfma_f32_16x16x32_bf16 v[124:127], v[144:147], v[214:217], v[124:127]
	global_load_lds_dwordx4 v[198:199], off
	v_mfma_f32_16x16x32_bf16 v[120:123], v[174:177], v[214:217], v[120:123]
	v_lshl_add_u64 v[198:199], s[90:91], 0, v[130:131]
	v_mfma_f32_16x16x32_bf16 v[108:111], v[144:147], v[222:225], v[108:111]
	s_mov_b32 m0, s71
	v_mfma_f32_16x16x32_bf16 v[104:107], v[174:177], v[222:225], v[104:107]
	global_load_lds_dwordx4 v[198:199], off
	v_mfma_f32_16x16x32_bf16 v[92:95], v[144:147], v[230:233], v[92:95]
	v_mfma_f32_16x16x32_bf16 v[88:91], v[174:177], v[230:233], v[88:91]
	v_mfma_f32_16x16x32_bf16 v[76:79], v[144:147], v[238:241], v[76:79]
	v_mfma_f32_16x16x32_bf16 v[72:75], v[174:177], v[238:241], v[72:75]
	v_mfma_f32_16x16x32_bf16 v[124:127], v[156:159], v[218:221], v[124:127]
	v_mfma_f32_16x16x32_bf16 v[120:123], v[178:181], v[218:221], v[120:123]
	v_mfma_f32_16x16x32_bf16 v[108:111], v[156:159], v[226:229], v[108:111]
	v_mfma_f32_16x16x32_bf16 v[104:107], v[178:181], v[226:229], v[104:107]
	v_mfma_f32_16x16x32_bf16 v[92:95], v[156:159], v[234:237], v[92:95]
	v_mfma_f32_16x16x32_bf16 v[88:91], v[178:181], v[234:237], v[88:91]
	v_mfma_f32_16x16x32_bf16 v[76:79], v[156:159], v[242:245], v[76:79]
	v_mfma_f32_16x16x32_bf16 v[72:75], v[178:181], v[242:245], v[72:75]
	s_setprio 0
	s_setprio 1
	v_mfma_f32_16x16x32_bf16 v[116:119], v[182:185], v[214:217], v[116:119]
	v_mfma_f32_16x16x32_bf16 v[112:115], v[206:209], v[214:217], v[112:115]
	v_mfma_f32_16x16x32_bf16 v[100:103], v[182:185], v[222:225], v[100:103]
	v_mfma_f32_16x16x32_bf16 v[96:99], v[206:209], v[222:225], v[96:99]
	v_mfma_f32_16x16x32_bf16 v[84:87], v[182:185], v[230:233], v[84:87]
	v_mfma_f32_16x16x32_bf16 v[80:83], v[206:209], v[230:233], v[80:83]
	v_mfma_f32_16x16x32_bf16 v[68:71], v[182:185], v[238:241], v[68:71]
	v_mfma_f32_16x16x32_bf16 v[64:67], v[206:209], v[238:241], v[64:67]
	s_barrier
; #define PG8_STAGE(bufoff, gbase, voff) do { _Pragma("unroll") for (int _i = 0; _i < 2; ++_i) \
;         __builtin_amdgcn_global_load_lds((const unsigned*)((const char*)(gbase) + (voff)[_i]), (PG8_LAS unsigned*)(lds + (bufoff) + ldsw + _i * 8192), 16, 0, 0); } while (0)
; #define PG8_LDA(dst, b, h) do { _Pragma("unroll") for (int m = 0; m < 4; ++m) _Pragma("unroll") for (int k = 0; k < 2; ++k) dst[m][k] = *(const PG8_LAS bf16x8*)(lds + PG8_SA(b, h) + aoff + m * 2048 + k * 1024); } while (0)
; #define PG8_MMA(ai, bj, At, Bt) do { __builtin_amdgcn_s_setprio(1); _Pragma("unroll") for (int m = 0; m < 4; ++m) _Pragma("unroll") for (int n = 0; n < 2; ++n) _Pragma("unroll") for (int k = 0; k < 2; ++k) \
;         acc[ai][bj][m][n] = __builtin_amdgcn_mfma_f32_16x16x32_bf16(Bt[n][k], At[m][k], acc[ai][bj][m][n], 0, 0, 0); __builtin_amdgcn_s_setprio(0); } while (0)
; #define PG8_WAIT_V(n) asm volatile("s_waitcnt vmcnt(" #n ")" ::: "memory")
; #define PG8_WAIT_L(n) asm volatile("s_waitcnt lgkmcnt(" #n ")" ::: "memory")
; #define PG8_BAR __builtin_amdgcn_s_barrier()
; #define PG8_SCHED __builtin_amdgcn_sched_barrier(0)
; template <class Epi, class Sched, bool ALIGN_EPI = false, bool SP2 = false>
; __device__ __forceinline__ void gemm_phase(PG8_LAS unsigned char* lds, const Gemm g, const Sched& S, const Epi& E) {
;     ...
;             PG8_WAIT_V(8); PG8_WAIT_L(0); PG8_BAR; PG8_MMA(0, 0, At, B0); PG8_MMA(0, 1, At, B1); PG8_BAR; PG8_SCHED;
;             PG8_LDA(At, 1, 1); PG8_STAGE(PG8_SB(1, 0), b3, voffB); PG8_STAGE(PG8_SB(1, 1), b3 + hstep, voffB); PG8_STAGE(PG8_SA(1, 0), a3, voffA);
;             PG8_WAIT_V(8); PG8_WAIT_L(0); PG8_BAR; PG8_MMA(1, 0, At, B0); PG8_MMA(1, 1, At, B1); PG8_BAR; PG8_SCHED;
	s_setprio 2
	v_mfma_f32_16x16x32_bf16 v[116:119], v[186:189], v[218:221], v[116:119]
	v_mfma_f32_16x16x32_bf16 v[112:115], v[210:213], v[218:221], v[112:115]
	v_mfma_f32_16x16x32_bf16 v[100:103], v[186:189], v[226:229], v[100:103]
	v_mfma_f32_16x16x32_bf16 v[96:99], v[210:213], v[226:229], v[96:99]
	v_mfma_f32_16x16x32_bf16 v[84:87], v[186:189], v[234:237], v[84:87]
	v_mfma_f32_16x16x32_bf16 v[80:83], v[210:213], v[234:237], v[80:83]
	v_mfma_f32_16x16x32_bf16 v[68:71], v[186:189], v[242:245], v[68:71]
	v_mfma_f32_16x16x32_bf16 v[64:67], v[210:213], v[242:245], v[64:67]
	s_setprio 0
	s_add_i32 s29, s29, s25
	v_lshl_add_u64 v[198:199], v[246:247], 0, s[58:59]
	s_mov_b32 m0, s29
	ds_read_b128 v[214:217], v154 offset:49152
	ds_read_b128 v[218:221], v154 offset:50176
	ds_read_b128 v[222:225], v154 offset:51200
	ds_read_b128 v[226:229], v154 offset:52224
	ds_read_b128 v[230:233], v154 offset:53248
	ds_read_b128 v[234:237], v154 offset:54272
	ds_read_b128 v[238:241], v154 offset:55296
	ds_read_b128 v[242:245], v154 offset:56320
	s_waitcnt vmcnt(2)
	s_nop 0
	s_barrier
	s_setprio 1
	s_waitcnt lgkmcnt(0)
	v_mfma_f32_16x16x32_bf16 v[60:63], v[144:147], v[214:217], v[60:63]
	global_load_lds_dwordx4 v[198:199], off
	v_mfma_f32_16x16x32_bf16 v[56:59], v[174:177], v[214:217], v[56:59]
	s_add_i32 m0, s29, 0x2000
	v_mfma_f32_16x16x32_bf16 v[44:47], v[144:147], v[222:225], v[44:47]
	s_add_u32 s20, s20, 0x80080
	v_mfma_f32_16x16x32_bf16 v[40:43], v[174:177], v[222:225], v[40:43]
	v_lshl_add_u64 v[198:199], v[248:249], 0, s[58:59]
	v_mfma_f32_16x16x32_bf16 v[28:31], v[144:147], v[230:233], v[28:31]
	s_addc_u32 s21, s21, 0
	v_mfma_f32_16x16x32_bf16 v[24:27], v[174:177], v[230:233], v[24:27]
	s_add_i32 s29, s46, s25
	v_mfma_f32_16x16x32_bf16 v[12:15], v[144:147], v[238:241], v[12:15]
	global_load_lds_dwordx4 v[198:199], off
	v_mfma_f32_16x16x32_bf16 v[8:11], v[174:177], v[238:241], v[8:11]
	v_lshl_add_u64 v[198:199], s[20:21], 0, v[132:133]
	v_mfma_f32_16x16x32_bf16 v[60:63], v[156:159], v[218:221], v[60:63]
	s_mov_b32 m0, s29
	v_mfma_f32_16x16x32_bf16 v[56:59], v[178:181], v[218:221], v[56:59]
	v_lshl_add_u64 v[196:197], v[196:197], 0, s[58:59]
	v_mfma_f32_16x16x32_bf16 v[44:47], v[156:159], v[226:229], v[44:47]
	global_load_lds_dwordx4 v[198:199], off
	v_mfma_f32_16x16x32_bf16 v[40:43], v[178:181], v[226:229], v[40:43]
	v_lshl_add_u64 v[198:199], s[20:21], 0, v[128:129]
	v_mfma_f32_16x16x32_bf16 v[28:31], v[156:159], v[234:237], v[28:31]
	s_add_i32 m0, s29, 0x2000
	v_mfma_f32_16x16x32_bf16 v[24:27], v[178:181], v[234:237], v[24:27]
	global_load_lds_dwordx4 v[198:199], off
	v_mfma_f32_16x16x32_bf16 v[12:15], v[156:159], v[242:245], v[12:15]
	v_lshl_add_u64 v[198:199], v[250:251], 0, s[58:59]
	v_mfma_f32_16x16x32_bf16 v[8:11], v[178:181], v[242:245], v[8:11]
	s_mov_b32 m0, s72
	s_setprio 0
	s_setprio 1
	v_mfma_f32_16x16x32_bf16 v[52:55], v[182:185], v[214:217], v[52:55]
	global_load_lds_dwordx4 v[198:199], off
	v_mfma_f32_16x16x32_bf16 v[48:51], v[206:209], v[214:217], v[48:51]
	s_mov_b32 m0, s73
	v_mfma_f32_16x16x32_bf16 v[36:39], v[182:185], v[222:225], v[36:39]
	global_load_lds_dwordx4 v[196:197], off
	v_mfma_f32_16x16x32_bf16 v[32:35], v[206:209], v[222:225], v[32:35]
	v_mfma_f32_16x16x32_bf16 v[20:23], v[182:185], v[230:233], v[20:23]
	v_mfma_f32_16x16x32_bf16 v[16:19], v[206:209], v[230:233], v[16:19]
	v_mfma_f32_16x16x32_bf16 v[4:7], v[182:185], v[238:241], v[4:7]
	v_mfma_f32_16x16x32_bf16 v[0:3], v[206:209], v[238:241], v[0:3]
	s_barrier
	s_setprio 2
	v_mfma_f32_16x16x32_bf16 v[52:55], v[186:189], v[218:221], v[52:55]
	v_mfma_f32_16x16x32_bf16 v[48:51], v[210:213], v[218:221], v[48:51]
	v_mfma_f32_16x16x32_bf16 v[36:39], v[186:189], v[226:229], v[36:39]
	v_mfma_f32_16x16x32_bf16 v[32:35], v[210:213], v[226:229], v[32:35]
	v_mfma_f32_16x16x32_bf16 v[20:23], v[186:189], v[234:237], v[20:23]
	v_mfma_f32_16x16x32_bf16 v[16:19], v[210:213], v[234:237], v[16:19]
	v_mfma_f32_16x16x32_bf16 v[4:7], v[186:189], v[242:245], v[4:7]
	v_mfma_f32_16x16x32_bf16 v[0:3], v[210:213], v[242:245], v[0:3]
	s_setprio 0
	s_add_i32 s28, s28, 2
	s_add_u32 s83, s83, 0x100
	s_addc_u32 s92, s92, 0
	s_add_u32 s88, s88, 0x100
	s_addc_u32 s89, s89, 0
	s_cmp_gt_u32 s28, 29
	s_cbranch_scc0 .LBB0_138
	s_and_b64 vcc, exec, s[42:43]
	s_cbranch_vccz .LBB0_143
	s_barrier
	v_lshl_add_u32 v155, s77, 8, v148
	s_cmp_gt_i32 s76, 7
	s_mov_b64 s[20:21], -1
	s_cbranch_scc1 .LBB0_144

; #define PG8_STAGE(bufoff, gbase, voff) do { _Pragma("unroll") for (int _i = 0; _i < 2; ++_i) \
;         __builtin_amdgcn_global_load_lds((const unsigned*)((const char*)(gbase) + (voff)[_i]), (PG8_LAS unsigned*)(lds + (bufoff) + ldsw + _i * 8192), 16, 0, 0); } while (0)
; #define PG8_LDA(dst, b, h) do { _Pragma("unroll") for (int m = 0; m < 4; ++m) _Pragma("unroll") for (int k = 0; k < 2; ++k) dst[m][k] = *(const PG8_LAS bf16x8*)(lds + PG8_SA(b, h) + aoff + m * 2048 + k * 1024); } while (0)
; #define PG8_LDB(dst, b, h) do { _Pragma("unroll") for (int n = 0; n < 2; ++n) _Pragma("unroll") for (int k = 0; k < 2; ++k) dst[n][k] = *(const PG8_LAS bf16x8*)(lds + PG8_SB(b, h) + boff + n * 2048 + k * 1024); } while (0)
; #define PG8_MMA(ai, bj, At, Bt) do { __builtin_amdgcn_s_setprio(1); _Pragma("unroll") for (int m = 0; m < 4; ++m) _Pragma("unroll") for (int n = 0; n < 2; ++n) _Pragma("unroll") for (int k = 0; k < 2; ++k) \
;         acc[ai][bj][m][n] = __builtin_amdgcn_mfma_f32_16x16x32_bf16(Bt[n][k], At[m][k], acc[ai][bj][m][n], 0, 0, 0); __builtin_amdgcn_s_setprio(0); } while (0)
; #define PG8_WAIT_V(n) asm volatile("s_waitcnt vmcnt(" #n ")" ::: "memory")
; #define PG8_WAIT_L(n) asm volatile("s_waitcnt lgkmcnt(" #n ")" ::: "memory")
; #define PG8_BAR __builtin_amdgcn_s_barrier()
; #define PG8_SCHED __builtin_amdgcn_sched_barrier(0)
; template <class Epi, class Sched, bool ALIGN_EPI = false, bool SP2 = false>
; __device__ __forceinline__ void gemm_phase(PG8_LAS unsigned char* lds, const Gemm g, const Sched& S, const Epi& E) {
;     ...
;             const char* a2 = last ? nA : cA + (size_t)(t + 2) * kstep; const char* b2 = last ? nB : cB + (size_t)(t + 2) * kstep;
;             const char* a3 = a2 + kstep; const char* b3 = b2 + kstep;
;             if (last && has_next) S.a_ready(nxt);
;             if constexpr (SP2) {
;             PG8_LDB(B0, 0, 0); PG8_LDB(B1, 0, 1); PG8_SCHED; PG8_LDA(At, 0, 0); PG8_STAGE(PG8_SA(1, 1), a1 + hstep, voffA);
;             PG8_WAIT_V(8); PG8_WAIT_L(0); PG8_BAR; PG8_MMA(0, 0, At, B0); PG8_MMA(0, 1, At, B1); PG8_BAR; PG8_SCHED;
;             PG8_LDA(At, 0, 1); PG8_STAGE(PG8_SB(0, 0), b2, voffB); PG8_STAGE(PG8_SB(0, 1), b2 + hstep, voffB); PG8_STAGE(PG8_SA(0, 0), a2, voffA);
;             PG8_WAIT_V(8); PG8_WAIT_L(0); PG8_BAR; PG8_MMA(1, 0, At, B0); PG8_MMA(1, 1, At, B1); PG8_BAR; PG8_SCHED;
.LBB0_316:
	s_add_u32 s28, vcc_lo, 0xfff80080
	s_addc_u32 s29, vcc_hi, -1
	s_add_i32 s46, 0, 0x10000
	s_cmp_eq_u32 s89, 28
	s_cselect_b32 s29, s76, s29
	s_cselect_b32 s28, s77, s28
	s_cselect_b32 s93, s78, s87
	s_cselect_b32 s92, s79, s81
	s_add_i32 s95, 0, 0x14000
	v_add_u32_e32 v140, s46, v211
	v_add_u32_e32 v182, s95, v211
	ds_read_b128 v[128:131], v140
	ds_read_b128 v[132:135], v140 offset:1024
	ds_read_b128 v[136:139], v140 offset:2048
	ds_read_b128 v[140:143], v140 offset:3072
	ds_read_b128 v[144:147], v182
	ds_read_b128 v[148:151], v182 offset:1024
	ds_read_b128 v[178:181], v182 offset:2048
	ds_read_b128 v[182:185], v182 offset:3072
	v_lshl_add_u64 v[196:197], vcc, 0, v[174:175]
	s_add_i32 m0, s30, 0xc000
	ds_read_b128 v[186:189], v213
	ds_read_b128 v[214:217], v213 offset:1024
	ds_read_b128 v[218:221], v213 offset:2048
	ds_read_b128 v[222:225], v213 offset:3072
	ds_read_b128 v[226:229], v213 offset:4096
	ds_read_b128 v[230:233], v213 offset:5120
	ds_read_b128 v[234:237], v213 offset:6144
	ds_read_b128 v[238:241], v213 offset:7168
	s_waitcnt vmcnt(6)
	s_nop 0
	s_barrier
	s_setprio 1
	s_waitcnt lgkmcnt(0)
	v_mfma_f32_16x16x32_bf16 v[124:127], v[128:131], v[186:189], v[124:127]
	global_load_lds_dwordx4 v[196:197], off
	v_mfma_f32_16x16x32_bf16 v[120:123], v[136:139], v[186:189], v[120:123]
	v_lshl_add_u64 v[196:197], vcc, 0, v[176:177]
	v_mfma_f32_16x16x32_bf16 v[108:111], v[128:131], v[218:221], v[108:111]
	s_add_i32 m0, s30, 0xe000
	v_mfma_f32_16x16x32_bf16 v[104:107], v[136:139], v[218:221], v[104:107]
	global_load_lds_dwordx4 v[196:197], off
	v_mfma_f32_16x16x32_bf16 v[92:95], v[128:131], v[226:229], v[92:95]
	v_mfma_f32_16x16x32_bf16 v[88:91], v[136:139], v[226:229], v[88:91]
	v_mfma_f32_16x16x32_bf16 v[76:79], v[128:131], v[234:237], v[76:79]
	v_mfma_f32_16x16x32_bf16 v[72:75], v[136:139], v[234:237], v[72:75]
	v_mfma_f32_16x16x32_bf16 v[124:127], v[132:135], v[214:217], v[124:127]
	v_mfma_f32_16x16x32_bf16 v[120:123], v[140:143], v[214:217], v[120:123]
	v_mfma_f32_16x16x32_bf16 v[108:111], v[132:135], v[222:225], v[108:111]
	v_mfma_f32_16x16x32_bf16 v[104:107], v[140:143], v[222:225], v[104:107]
	v_mfma_f32_16x16x32_bf16 v[92:95], v[132:135], v[230:233], v[92:95]
	v_mfma_f32_16x16x32_bf16 v[88:91], v[140:143], v[230:233], v[88:91]
	v_mfma_f32_16x16x32_bf16 v[76:79], v[132:135], v[238:241], v[76:79]
	v_mfma_f32_16x16x32_bf16 v[72:75], v[140:143], v[238:241], v[72:75]
	s_setprio 0
	s_setprio 1
	v_mfma_f32_16x16x32_bf16 v[116:119], v[144:147], v[186:189], v[116:119]
	v_mfma_f32_16x16x32_bf16 v[112:115], v[178:181], v[186:189], v[112:115]
	v_mfma_f32_16x16x32_bf16 v[100:103], v[144:147], v[218:221], v[100:103]
	v_mfma_f32_16x16x32_bf16 v[96:99], v[178:181], v[218:221], v[96:99]
	v_mfma_f32_16x16x32_bf16 v[84:87], v[144:147], v[226:229], v[84:87]
	v_mfma_f32_16x16x32_bf16 v[80:83], v[178:181], v[226:229], v[80:83]
	v_mfma_f32_16x16x32_bf16 v[68:71], v[144:147], v[234:237], v[68:71]
	v_mfma_f32_16x16x32_bf16 v[64:67], v[178:181], v[234:237], v[64:67]
	s_barrier
	s_setprio 2
	v_mfma_f32_16x16x32_bf16 v[116:119], v[148:151], v[214:217], v[116:119]
	v_mfma_f32_16x16x32_bf16 v[112:115], v[182:185], v[214:217], v[112:115]
	v_mfma_f32_16x16x32_bf16 v[100:103], v[148:151], v[222:225], v[100:103]
	v_mfma_f32_16x16x32_bf16 v[96:99], v[182:185], v[222:225], v[96:99]
	v_mfma_f32_16x16x32_bf16 v[84:87], v[148:151], v[230:233], v[84:87]
	v_mfma_f32_16x16x32_bf16 v[80:83], v[182:185], v[230:233], v[80:83]
	v_mfma_f32_16x16x32_bf16 v[68:71], v[148:151], v[238:241], v[68:71]
	v_mfma_f32_16x16x32_bf16 v[64:67], v[182:185], v[238:241], v[64:67]
	s_setprio 0
	s_add_i32 s46, s46, s25
	v_lshl_add_u64 v[196:197], s[92:93], 0, v[162:163]
	s_mov_b32 m0, s46
	ds_read_b128 v[186:189], v213 offset:16384
	ds_read_b128 v[214:217], v213 offset:17408
	ds_read_b128 v[218:221], v213 offset:18432
	ds_read_b128 v[222:225], v213 offset:19456
	ds_read_b128 v[226:229], v213 offset:20480
	ds_read_b128 v[230:233], v213 offset:21504
	ds_read_b128 v[234:237], v213 offset:22528
	ds_read_b128 v[238:241], v213 offset:23552
	s_waitcnt vmcnt(2)
	s_nop 0
	s_barrier
	s_setprio 1
	s_waitcnt lgkmcnt(0)
	v_mfma_f32_16x16x32_bf16 v[60:63], v[128:131], v[186:189], v[60:63]
	global_load_lds_dwordx4 v[196:197], off
	v_mfma_f32_16x16x32_bf16 v[56:59], v[136:139], v[186:189], v[56:59]
	s_add_i32 m0, s46, 0x2000
	v_mfma_f32_16x16x32_bf16 v[44:47], v[128:131], v[218:221], v[44:47]
	s_add_u32 s46, s92, 0x80000
	v_mfma_f32_16x16x32_bf16 v[40:43], v[136:139], v[218:221], v[40:43]
	v_lshl_add_u64 v[198:199], s[92:93], 0, v[152:153]
	v_mfma_f32_16x16x32_bf16 v[28:31], v[128:131], v[226:229], v[28:31]
	s_addc_u32 s47, s93, 0
	v_mfma_f32_16x16x32_bf16 v[24:27], v[136:139], v[226:229], v[24:27]
	s_add_i32 s95, s95, s25
	v_mfma_f32_16x16x32_bf16 v[12:15], v[128:131], v[234:237], v[12:15]
	global_load_lds_dwordx4 v[198:199], off
	v_mfma_f32_16x16x32_bf16 v[8:11], v[136:139], v[234:237], v[8:11]
	v_lshl_add_u64 v[242:243], s[46:47], 0, v[162:163]
	v_mfma_f32_16x16x32_bf16 v[60:63], v[132:135], v[214:217], v[60:63]
	s_mov_b32 m0, s95
	v_mfma_f32_16x16x32_bf16 v[56:59], v[140:143], v[214:217], v[56:59]
	v_lshl_add_u64 v[244:245], s[28:29], 0, v[154:155]
	v_mfma_f32_16x16x32_bf16 v[44:47], v[132:135], v[222:225], v[44:47]
	global_load_lds_dwordx4 v[242:243], off
	v_mfma_f32_16x16x32_bf16 v[40:43], v[140:143], v[222:225], v[40:43]
	v_lshl_add_u64 v[242:243], s[46:47], 0, v[152:153]
	v_mfma_f32_16x16x32_bf16 v[28:31], v[132:135], v[230:233], v[28:31]
	s_add_i32 m0, s95, 0x2000
	v_mfma_f32_16x16x32_bf16 v[24:27], v[140:143], v[230:233], v[24:27]
	global_load_lds_dwordx4 v[242:243], off
	v_mfma_f32_16x16x32_bf16 v[12:15], v[132:135], v[238:241], v[12:15]
	v_lshl_add_u64 v[242:243], s[28:29], 0, v[156:157]
	v_mfma_f32_16x16x32_bf16 v[8:11], v[140:143], v[238:241], v[8:11]
	s_mov_b32 m0, s30
	s_setprio 0
	s_setprio 1
	v_mfma_f32_16x16x32_bf16 v[52:55], v[144:147], v[186:189], v[52:55]
	global_load_lds_dwordx4 v[242:243], off
	v_mfma_f32_16x16x32_bf16 v[48:51], v[178:181], v[186:189], v[48:51]
	s_mov_b32 m0, s31
	v_mfma_f32_16x16x32_bf16 v[36:39], v[144:147], v[218:221], v[36:39]
	global_load_lds_dwordx4 v[244:245], off
	v_mfma_f32_16x16x32_bf16 v[32:35], v[178:181], v[218:221], v[32:35]
	v_mfma_f32_16x16x32_bf16 v[20:23], v[144:147], v[226:229], v[20:23]
	v_mfma_f32_16x16x32_bf16 v[16:19], v[178:181], v[226:229], v[16:19]
	v_mfma_f32_16x16x32_bf16 v[4:7], v[144:147], v[234:237], v[4:7]
	v_mfma_f32_16x16x32_bf16 v[0:3], v[178:181], v[234:237], v[0:3]
	s_barrier
; #define PG8_STAGE(bufoff, gbase, voff) do { _Pragma("unroll") for (int _i = 0; _i < 2; ++_i) \
;         __builtin_amdgcn_global_load_lds((const unsigned*)((const char*)(gbase) + (voff)[_i]), (PG8_LAS unsigned*)(lds + (bufoff) + ldsw + _i * 8192), 16, 0, 0); } while (0)
; #define PG8_LDA(dst, b, h) do { _Pragma("unroll") for (int m = 0; m < 4; ++m) _Pragma("unroll") for (int k = 0; k < 2; ++k) dst[m][k] = *(const PG8_LAS bf16x8*)(lds + PG8_SA(b, h) + aoff + m * 2048 + k * 1024); } while (0)
; #define PG8_LDB(dst, b, h) do { _Pragma("unroll") for (int n = 0; n < 2; ++n) _Pragma("unroll") for (int k = 0; k < 2; ++k) dst[n][k] = *(const PG8_LAS bf16x8*)(lds + PG8_SB(b, h) + boff + n * 2048 + k * 1024); } while (0)
; #define PG8_MMA(ai, bj, At, Bt) do { __builtin_amdgcn_s_setprio(1); _Pragma("unroll") for (int m = 0; m < 4; ++m) _Pragma("unroll") for (int n = 0; n < 2; ++n) _Pragma("unroll") for (int k = 0; k < 2; ++k) \
;         acc[ai][bj][m][n] = __builtin_amdgcn_mfma_f32_16x16x32_bf16(Bt[n][k], At[m][k], acc[ai][bj][m][n], 0, 0, 0); __builtin_amdgcn_s_setprio(0); } while (0)
; #define PG8_WAIT_V(n) asm volatile("s_waitcnt vmcnt(" #n ")" ::: "memory")
; #define PG8_WAIT_L(n) asm volatile("s_waitcnt lgkmcnt(" #n ")" ::: "memory")
; #define PG8_BAR __builtin_amdgcn_s_barrier()
; #define PG8_SCHED __builtin_amdgcn_sched_barrier(0)
; template <class Epi, class Sched, bool ALIGN_EPI = false, bool SP2 = false>
; __device__ __forceinline__ void gemm_phase(PG8_LAS unsigned char* lds, const Gemm g, const Sched& S, const Epi& E) {
;     ...
;             PG8_WAIT_V(8); PG8_WAIT_L(0); PG8_BAR; PG8_MMA(1, 0, At, B0); PG8_MMA(1, 1, At, B1); PG8_BAR; PG8_SCHED;
;             PG8_LDB(B0, 1, 0); PG8_LDB(B1, 1, 1); PG8_SCHED; PG8_LDA(At, 1, 0); PG8_STAGE(PG8_SA(0, 1), a2 + hstep, voffA);
;             PG8_WAIT_V(8); PG8_WAIT_L(0); PG8_BAR; PG8_MMA(0, 0, At, B0); PG8_MMA(0, 1, At, B1); PG8_BAR; PG8_SCHED;
	s_setprio 2
	v_mfma_f32_16x16x32_bf16 v[52:55], v[148:151], v[214:217], v[52:55]
	v_mfma_f32_16x16x32_bf16 v[48:51], v[182:185], v[214:217], v[48:51]
	v_mfma_f32_16x16x32_bf16 v[36:39], v[148:151], v[222:225], v[36:39]
	v_mfma_f32_16x16x32_bf16 v[32:35], v[182:185], v[222:225], v[32:35]
	v_mfma_f32_16x16x32_bf16 v[20:23], v[148:151], v[230:233], v[20:23]
	v_mfma_f32_16x16x32_bf16 v[16:19], v[182:185], v[230:233], v[16:19]
	v_mfma_f32_16x16x32_bf16 v[4:7], v[148:151], v[238:241], v[4:7]
	v_mfma_f32_16x16x32_bf16 v[0:3], v[182:185], v[238:241], v[0:3]
	s_setprio 0
	s_add_i32 s46, 0, 0x18000
	s_add_i32 s47, 0, 0x1c000
	v_add_u32_e32 v140, s46, v211
	v_add_u32_e32 v182, s47, v211
	ds_read_b128 v[128:131], v140
	ds_read_b128 v[132:135], v140 offset:1024
	ds_read_b128 v[136:139], v140 offset:2048
	ds_read_b128 v[140:143], v140 offset:3072
	ds_read_b128 v[144:147], v182
	ds_read_b128 v[148:151], v182 offset:1024
	ds_read_b128 v[178:181], v182 offset:2048
	ds_read_b128 v[182:185], v182 offset:3072
	s_add_u32 s28, s28, 0x80000
	s_addc_u32 s29, s29, 0
	s_mov_b32 m0, s70
	v_lshl_add_u64 v[246:247], s[28:29], 0, v[156:157]
	ds_read_b128 v[186:189], v213 offset:32768
	ds_read_b128 v[214:217], v213 offset:33792
	ds_read_b128 v[218:221], v213 offset:34816
	ds_read_b128 v[222:225], v213 offset:35840
	ds_read_b128 v[226:229], v213 offset:36864
	ds_read_b128 v[230:233], v213 offset:37888
	ds_read_b128 v[234:237], v213 offset:38912
	ds_read_b128 v[238:241], v213 offset:39936
	s_waitcnt vmcnt(6)
	s_nop 0
	s_barrier
	s_setprio 1
	s_waitcnt lgkmcnt(0)
	v_mfma_f32_16x16x32_bf16 v[124:127], v[128:131], v[186:189], v[124:127]
	global_load_lds_dwordx4 v[246:247], off
	v_mfma_f32_16x16x32_bf16 v[120:123], v[136:139], v[186:189], v[120:123]
	v_lshl_add_u64 v[246:247], s[28:29], 0, v[154:155]
	v_mfma_f32_16x16x32_bf16 v[108:111], v[128:131], v[218:221], v[108:111]
	s_mov_b32 m0, s71
	v_mfma_f32_16x16x32_bf16 v[104:107], v[136:139], v[218:221], v[104:107]
	global_load_lds_dwordx4 v[246:247], off
	v_mfma_f32_16x16x32_bf16 v[92:95], v[128:131], v[226:229], v[92:95]
	v_mfma_f32_16x16x32_bf16 v[88:91], v[136:139], v[226:229], v[88:91]
	v_mfma_f32_16x16x32_bf16 v[76:79], v[128:131], v[234:237], v[76:79]
	v_mfma_f32_16x16x32_bf16 v[72:75], v[136:139], v[234:237], v[72:75]
	v_mfma_f32_16x16x32_bf16 v[124:127], v[132:135], v[214:217], v[124:127]
	v_mfma_f32_16x16x32_bf16 v[120:123], v[140:143], v[214:217], v[120:123]
	v_mfma_f32_16x16x32_bf16 v[108:111], v[132:135], v[222:225], v[108:111]
	v_mfma_f32_16x16x32_bf16 v[104:107], v[140:143], v[222:225], v[104:107]
	v_mfma_f32_16x16x32_bf16 v[92:95], v[132:135], v[230:233], v[92:95]
	v_mfma_f32_16x16x32_bf16 v[88:91], v[140:143], v[230:233], v[88:91]
	v_mfma_f32_16x16x32_bf16 v[76:79], v[132:135], v[238:241], v[76:79]
	v_mfma_f32_16x16x32_bf16 v[72:75], v[140:143], v[238:241], v[72:75]
	s_setprio 0
	s_setprio 1
	v_mfma_f32_16x16x32_bf16 v[116:119], v[144:147], v[186:189], v[116:119]
	v_mfma_f32_16x16x32_bf16 v[112:115], v[178:181], v[186:189], v[112:115]
	v_mfma_f32_16x16x32_bf16 v[100:103], v[144:147], v[218:221], v[100:103]
	v_mfma_f32_16x16x32_bf16 v[96:99], v[178:181], v[218:221], v[96:99]
	v_mfma_f32_16x16x32_bf16 v[84:87], v[144:147], v[226:229], v[84:87]
	v_mfma_f32_16x16x32_bf16 v[80:83], v[178:181], v[226:229], v[80:83]
	v_mfma_f32_16x16x32_bf16 v[68:71], v[144:147], v[234:237], v[68:71]
	v_mfma_f32_16x16x32_bf16 v[64:67], v[178:181], v[234:237], v[64:67]
	s_barrier
; #define PG8_STAGE(bufoff, gbase, voff) do { _Pragma("unroll") for (int _i = 0; _i < 2; ++_i) \
;         __builtin_amdgcn_global_load_lds((const unsigned*)((const char*)(gbase) + (voff)[_i]), (PG8_LAS unsigned*)(lds + (bufoff) + ldsw + _i * 8192), 16, 0, 0); } while (0)
; #define PG8_LDA(dst, b, h) do { _Pragma("unroll") for (int m = 0; m < 4; ++m) _Pragma("unroll") for (int k = 0; k < 2; ++k) dst[m][k] = *(const PG8_LAS bf16x8*)(lds + PG8_SA(b, h) + aoff + m * 2048 + k * 1024); } while (0)
; #define PG8_MMA(ai, bj, At, Bt) do { __builtin_amdgcn_s_setprio(1); _Pragma("unroll") for (int m = 0; m < 4; ++m) _Pragma("unroll") for (int n = 0; n < 2; ++n) _Pragma("unroll") for (int k = 0; k < 2; ++k) \
;         acc[ai][bj][m][n] = __builtin_amdgcn_mfma_f32_16x16x32_bf16(Bt[n][k], At[m][k], acc[ai][bj][m][n], 0, 0, 0); __builtin_amdgcn_s_setprio(0); } while (0)
; #define PG8_WAIT_V(n) asm volatile("s_waitcnt vmcnt(" #n ")" ::: "memory")
; #define PG8_WAIT_L(n) asm volatile("s_waitcnt lgkmcnt(" #n ")" ::: "memory")
; #define PG8_BAR __builtin_amdgcn_s_barrier()
; #define PG8_SCHED __builtin_amdgcn_sched_barrier(0)
; template <class Epi, class Sched, bool ALIGN_EPI = false, bool SP2 = false>
; __device__ __forceinline__ void gemm_phase(PG8_LAS unsigned char* lds, const Gemm g, const Sched& S, const Epi& E) {
;     ...
;             PG8_WAIT_V(8); PG8_WAIT_L(0); PG8_BAR; PG8_MMA(0, 0, At, B0); PG8_MMA(0, 1, At, B1); PG8_BAR; PG8_SCHED;
;             PG8_LDA(At, 1, 1); PG8_STAGE(PG8_SB(1, 0), b3, voffB); PG8_STAGE(PG8_SB(1, 1), b3 + hstep, voffB); PG8_STAGE(PG8_SA(1, 0), a3, voffA);
;             PG8_WAIT_V(8); PG8_WAIT_L(0); PG8_BAR; PG8_MMA(1, 0, At, B0); PG8_MMA(1, 1, At, B1); PG8_BAR; PG8_SCHED;
	s_setprio 2
	v_mfma_f32_16x16x32_bf16 v[116:119], v[148:151], v[214:217], v[116:119]
	v_mfma_f32_16x16x32_bf16 v[112:115], v[182:185], v[214:217], v[112:115]
	v_mfma_f32_16x16x32_bf16 v[100:103], v[148:151], v[222:225], v[100:103]
	v_mfma_f32_16x16x32_bf16 v[96:99], v[182:185], v[222:225], v[96:99]
	v_mfma_f32_16x16x32_bf16 v[84:87], v[148:151], v[230:233], v[84:87]
	v_mfma_f32_16x16x32_bf16 v[80:83], v[182:185], v[230:233], v[80:83]
	v_mfma_f32_16x16x32_bf16 v[68:71], v[148:151], v[238:241], v[68:71]
	v_mfma_f32_16x16x32_bf16 v[64:67], v[182:185], v[238:241], v[64:67]
	s_setprio 0
	s_add_i32 s28, s46, s25
	v_lshl_add_u64 v[196:197], v[196:197], 0, s[58:59]
	s_mov_b32 m0, s28
	ds_read_b128 v[186:189], v213 offset:49152
	ds_read_b128 v[214:217], v213 offset:50176
	ds_read_b128 v[218:221], v213 offset:51200
	ds_read_b128 v[222:225], v213 offset:52224
	ds_read_b128 v[226:229], v213 offset:53248
	ds_read_b128 v[230:233], v213 offset:54272
	ds_read_b128 v[234:237], v213 offset:55296
	ds_read_b128 v[238:241], v213 offset:56320
	s_waitcnt vmcnt(2)
	s_nop 0
	s_barrier
	s_setprio 1
	s_waitcnt lgkmcnt(0)
	v_mfma_f32_16x16x32_bf16 v[60:63], v[128:131], v[186:189], v[60:63]
	global_load_lds_dwordx4 v[196:197], off
	v_mfma_f32_16x16x32_bf16 v[56:59], v[136:139], v[186:189], v[56:59]
	s_add_i32 m0, s28, 0x2000
	v_mfma_f32_16x16x32_bf16 v[44:47], v[128:131], v[218:221], v[44:47]
	s_add_u32 s28, s92, 0x80080
	v_mfma_f32_16x16x32_bf16 v[40:43], v[136:139], v[218:221], v[40:43]
	v_lshl_add_u64 v[196:197], v[198:199], 0, s[58:59]
	v_mfma_f32_16x16x32_bf16 v[28:31], v[128:131], v[226:229], v[28:31]
	s_addc_u32 s29, s93, 0
	v_mfma_f32_16x16x32_bf16 v[24:27], v[136:139], v[226:229], v[24:27]
	s_add_i32 s46, s47, s25
	v_mfma_f32_16x16x32_bf16 v[12:15], v[128:131], v[234:237], v[12:15]
	global_load_lds_dwordx4 v[196:197], off
	v_mfma_f32_16x16x32_bf16 v[8:11], v[136:139], v[234:237], v[8:11]
	v_lshl_add_u64 v[196:197], s[28:29], 0, v[162:163]
	v_mfma_f32_16x16x32_bf16 v[60:63], v[132:135], v[214:217], v[60:63]
	s_mov_b32 m0, s46
	v_mfma_f32_16x16x32_bf16 v[56:59], v[140:143], v[214:217], v[56:59]
	global_load_lds_dwordx4 v[196:197], off
	v_mfma_f32_16x16x32_bf16 v[44:47], v[132:135], v[222:225], v[44:47]
	v_lshl_add_u64 v[196:197], s[28:29], 0, v[152:153]
	v_mfma_f32_16x16x32_bf16 v[40:43], v[140:143], v[222:225], v[40:43]
	s_add_i32 m0, s46, 0x2000
	v_mfma_f32_16x16x32_bf16 v[28:31], v[132:135], v[230:233], v[28:31]
	global_load_lds_dwordx4 v[196:197], off
	v_mfma_f32_16x16x32_bf16 v[24:27], v[140:143], v[230:233], v[24:27]
	v_lshl_add_u64 v[196:197], v[242:243], 0, s[58:59]
	v_mfma_f32_16x16x32_bf16 v[12:15], v[132:135], v[238:241], v[12:15]
	s_mov_b32 m0, s72
	v_mfma_f32_16x16x32_bf16 v[8:11], v[140:143], v[238:241], v[8:11]
	global_load_lds_dwordx4 v[196:197], off
	s_setprio 0
	s_setprio 1
	v_mfma_f32_16x16x32_bf16 v[52:55], v[144:147], v[186:189], v[52:55]
	v_lshl_add_u64 v[196:197], v[244:245], 0, s[58:59]
	v_mfma_f32_16x16x32_bf16 v[48:51], v[178:181], v[186:189], v[48:51]
	s_mov_b32 m0, s73
	v_mfma_f32_16x16x32_bf16 v[36:39], v[144:147], v[218:221], v[36:39]
	global_load_lds_dwordx4 v[196:197], off
	v_mfma_f32_16x16x32_bf16 v[32:35], v[178:181], v[218:221], v[32:35]
	v_mfma_f32_16x16x32_bf16 v[20:23], v[144:147], v[226:229], v[20:23]
	v_mfma_f32_16x16x32_bf16 v[16:19], v[178:181], v[226:229], v[16:19]
	v_mfma_f32_16x16x32_bf16 v[4:7], v[144:147], v[234:237], v[4:7]
	v_mfma_f32_16x16x32_bf16 v[0:3], v[178:181], v[234:237], v[0:3]
	s_barrier
	s_setprio 2
	v_mfma_f32_16x16x32_bf16 v[52:55], v[148:151], v[214:217], v[52:55]
	v_mfma_f32_16x16x32_bf16 v[48:51], v[182:185], v[214:217], v[48:51]
	v_mfma_f32_16x16x32_bf16 v[36:39], v[148:151], v[222:225], v[36:39]
	v_mfma_f32_16x16x32_bf16 v[32:35], v[182:185], v[222:225], v[32:35]
	v_mfma_f32_16x16x32_bf16 v[20:23], v[148:151], v[230:233], v[20:23]
	v_mfma_f32_16x16x32_bf16 v[16:19], v[182:185], v[230:233], v[16:19]
	v_mfma_f32_16x16x32_bf16 v[4:7], v[148:151], v[238:241], v[4:7]
	v_mfma_f32_16x16x32_bf16 v[0:3], v[182:185], v[238:241], v[0:3]
	s_setprio 0
	s_add_i32 s89, s89, 2
	s_add_u32 s81, s81, 0x100
	s_addc_u32 s87, s87, 0
	s_add_u32 vcc_lo, vcc_lo, 0x100
	s_addc_u32 vcc_hi, vcc_hi, 0
	s_cmp_gt_u32 s89, 29
	s_cbranch_scc0 .LBB0_316
	s_and_b64 vcc, exec, s[84:85]
	s_cbranch_vccz .LBB0_319
	s_barrier

; #define PG8_STAGE(bufoff, gbase, voff) do { _Pragma("unroll") for (int _i = 0; _i < 2; ++_i) \
;         __builtin_amdgcn_global_load_lds((const unsigned*)((const char*)(gbase) + (voff)[_i]), (PG8_LAS unsigned*)(lds + (bufoff) + ldsw + _i * 8192), 16, 0, 0); } while (0)
; #define PG8_LDA(dst, b, h) do { _Pragma("unroll") for (int m = 0; m < 4; ++m) _Pragma("unroll") for (int k = 0; k < 2; ++k) dst[m][k] = *(const PG8_LAS bf16x8*)(lds + PG8_SA(b, h) + aoff + m * 2048 + k * 1024); } while (0)
; #define PG8_LDB(dst, b, h) do { _Pragma("unroll") for (int n = 0; n < 2; ++n) _Pragma("unroll") for (int k = 0; k < 2; ++k) dst[n][k] = *(const PG8_LAS bf16x8*)(lds + PG8_SB(b, h) + boff + n * 2048 + k * 1024); } while (0)
; #define PG8_MMA(ai, bj, At, Bt) do { __builtin_amdgcn_s_setprio(1); _Pragma("unroll") for (int m = 0; m < 4; ++m) _Pragma("unroll") for (int n = 0; n < 2; ++n) _Pragma("unroll") for (int k = 0; k < 2; ++k) \
;         acc[ai][bj][m][n] = __builtin_amdgcn_mfma_f32_16x16x32_bf16(Bt[n][k], At[m][k], acc[ai][bj][m][n], 0, 0, 0); __builtin_amdgcn_s_setprio(0); } while (0)
; #define PG8_WAIT_V(n) asm volatile("s_waitcnt vmcnt(" #n ")" ::: "memory")
; #define PG8_WAIT_L(n) asm volatile("s_waitcnt lgkmcnt(" #n ")" ::: "memory")
; #define PG8_BAR __builtin_amdgcn_s_barrier()
; #define PG8_SCHED __builtin_amdgcn_sched_barrier(0)
; template <class Epi, class Sched, bool ALIGN_EPI = false, bool SP2 = false>
; __device__ __forceinline__ void gemm_phase(PG8_LAS unsigned char* lds, const Gemm g, const Sched& S, const Epi& E) {
;     ...
;             const char* a2 = last ? nA : cA + (size_t)(t + 2) * kstep; const char* b2 = last ? nB : cB + (size_t)(t + 2) * kstep;
;             const char* a3 = a2 + kstep; const char* b3 = b2 + kstep;
;             if (last && has_next) S.a_ready(nxt);
;             if constexpr (SP2) {
;             PG8_LDB(B0, 0, 0); PG8_LDB(B1, 0, 1); PG8_SCHED; PG8_LDA(At, 0, 0); PG8_STAGE(PG8_SA(1, 1), a1 + hstep, voffA);
;             PG8_WAIT_V(8); PG8_WAIT_L(0); PG8_BAR; PG8_MMA(0, 0, At, B0); PG8_MMA(0, 1, At, B1); PG8_BAR; PG8_SCHED;
;             PG8_LDA(At, 0, 1); PG8_STAGE(PG8_SB(0, 0), b2, voffB); PG8_STAGE(PG8_SB(0, 1), b2 + hstep, voffB); PG8_STAGE(PG8_SA(0, 0), a2, voffA);
;             PG8_WAIT_V(8); PG8_WAIT_L(0); PG8_BAR; PG8_MMA(1, 0, At, B0); PG8_MMA(1, 1, At, B1); PG8_BAR; PG8_SCHED;
.LBB0_368:
	s_add_u32 s20, s92, 0xfff80080
	s_addc_u32 s21, s93, -1
	s_add_i32 s46, 0, 0x10000
	s_cmp_eq_u32 s95, 28
	s_cselect_b32 s29, s78, s21
	s_cselect_b32 s28, s79, s20
	v_add_u32_e32 v138, s46, v141
	s_cselect_b32 s21, s81, s94
	s_cselect_b32 s20, s85, s87
	s_add_i32 vcc_lo, 0, 0x14000
	ds_read_b128 v[146:149], v138
	ds_read_b128 v[150:153], v138 offset:1024
	ds_read_b128 v[154:157], v138 offset:2048
	ds_read_b128 v[174:177], v138 offset:3072
	v_add_u32_e32 v138, vcc_lo, v141
	ds_read_b128 v[178:181], v138
	ds_read_b128 v[182:185], v138 offset:1024
	ds_read_b128 v[186:189], v138 offset:2048
	ds_read_b128 v[210:213], v138 offset:3072
	v_lshl_add_u64 v[138:139], s[92:93], 0, v[134:135]
	s_add_i32 m0, s30, 0xc000
	ds_read_b128 v[214:217], v144
	ds_read_b128 v[218:221], v144 offset:1024
	ds_read_b128 v[222:225], v144 offset:2048
	ds_read_b128 v[226:229], v144 offset:3072
	ds_read_b128 v[230:233], v144 offset:4096
	ds_read_b128 v[234:237], v144 offset:5120
	ds_read_b128 v[238:241], v144 offset:6144
	ds_read_b128 v[242:245], v144 offset:7168
	s_waitcnt vmcnt(6)
	s_nop 0
	s_barrier
	s_setprio 1
	s_waitcnt lgkmcnt(0)
	v_mfma_f32_16x16x32_bf16 v[124:127], v[146:149], v[214:217], v[124:127]
	global_load_lds_dwordx4 v[138:139], off
	v_mfma_f32_16x16x32_bf16 v[116:119], v[154:157], v[214:217], v[116:119]
	v_lshl_add_u64 v[138:139], s[92:93], 0, v[136:137]
	v_mfma_f32_16x16x32_bf16 v[108:111], v[146:149], v[222:225], v[108:111]
	s_add_i32 m0, s30, 0xe000
	v_mfma_f32_16x16x32_bf16 v[100:103], v[154:157], v[222:225], v[100:103]
	global_load_lds_dwordx4 v[138:139], off
	v_mfma_f32_16x16x32_bf16 v[92:95], v[146:149], v[230:233], v[92:95]
	v_mfma_f32_16x16x32_bf16 v[84:87], v[154:157], v[230:233], v[84:87]
	v_mfma_f32_16x16x32_bf16 v[76:79], v[146:149], v[238:241], v[76:79]
	v_mfma_f32_16x16x32_bf16 v[68:71], v[154:157], v[238:241], v[68:71]
	v_mfma_f32_16x16x32_bf16 v[124:127], v[150:153], v[218:221], v[124:127]
	v_mfma_f32_16x16x32_bf16 v[116:119], v[174:177], v[218:221], v[116:119]
	v_mfma_f32_16x16x32_bf16 v[108:111], v[150:153], v[226:229], v[108:111]
	v_mfma_f32_16x16x32_bf16 v[100:103], v[174:177], v[226:229], v[100:103]
	v_mfma_f32_16x16x32_bf16 v[92:95], v[150:153], v[234:237], v[92:95]
	v_mfma_f32_16x16x32_bf16 v[84:87], v[174:177], v[234:237], v[84:87]
	v_mfma_f32_16x16x32_bf16 v[76:79], v[150:153], v[242:245], v[76:79]
	v_mfma_f32_16x16x32_bf16 v[68:71], v[174:177], v[242:245], v[68:71]
	s_setprio 0
	s_setprio 1
	v_mfma_f32_16x16x32_bf16 v[120:123], v[178:181], v[214:217], v[120:123]
	v_mfma_f32_16x16x32_bf16 v[112:115], v[186:189], v[214:217], v[112:115]
	v_mfma_f32_16x16x32_bf16 v[104:107], v[178:181], v[222:225], v[104:107]
	v_mfma_f32_16x16x32_bf16 v[96:99], v[186:189], v[222:225], v[96:99]
	v_mfma_f32_16x16x32_bf16 v[88:91], v[178:181], v[230:233], v[88:91]
	v_mfma_f32_16x16x32_bf16 v[80:83], v[186:189], v[230:233], v[80:83]
	v_mfma_f32_16x16x32_bf16 v[72:75], v[178:181], v[238:241], v[72:75]
	v_mfma_f32_16x16x32_bf16 v[64:67], v[186:189], v[238:241], v[64:67]
	s_barrier
	s_setprio 2
	v_mfma_f32_16x16x32_bf16 v[120:123], v[182:185], v[218:221], v[120:123]
	v_mfma_f32_16x16x32_bf16 v[112:115], v[210:213], v[218:221], v[112:115]
	v_mfma_f32_16x16x32_bf16 v[104:107], v[182:185], v[226:229], v[104:107]
	v_mfma_f32_16x16x32_bf16 v[96:99], v[210:213], v[226:229], v[96:99]
	v_mfma_f32_16x16x32_bf16 v[88:91], v[182:185], v[234:237], v[88:91]
	v_mfma_f32_16x16x32_bf16 v[80:83], v[210:213], v[234:237], v[80:83]
	v_mfma_f32_16x16x32_bf16 v[72:75], v[182:185], v[242:245], v[72:75]
	v_mfma_f32_16x16x32_bf16 v[64:67], v[210:213], v[242:245], v[64:67]
	s_setprio 0
	s_add_i32 s46, s46, s25
	v_lshl_add_u64 v[138:139], s[20:21], 0, v[162:163]
	s_mov_b32 m0, s46
	ds_read_b128 v[214:217], v144 offset:16384
	ds_read_b128 v[218:221], v144 offset:17408
	ds_read_b128 v[222:225], v144 offset:18432
	ds_read_b128 v[226:229], v144 offset:19456
	ds_read_b128 v[230:233], v144 offset:20480
	ds_read_b128 v[234:237], v144 offset:21504
	ds_read_b128 v[238:241], v144 offset:22528
	ds_read_b128 v[242:245], v144 offset:23552
	s_waitcnt vmcnt(2)
	s_nop 0
	s_barrier
	s_setprio 1
	s_waitcnt lgkmcnt(0)
	v_mfma_f32_16x16x32_bf16 v[60:63], v[146:149], v[214:217], v[60:63]
	global_load_lds_dwordx4 v[138:139], off
	v_mfma_f32_16x16x32_bf16 v[52:55], v[154:157], v[214:217], v[52:55]
	s_add_i32 m0, s46, 0x2000
	v_mfma_f32_16x16x32_bf16 v[44:47], v[146:149], v[222:225], v[44:47]
	s_add_u32 s46, s20, 0x80000
	v_mfma_f32_16x16x32_bf16 v[36:39], v[154:157], v[222:225], v[36:39]
	v_lshl_add_u64 v[158:159], s[20:21], 0, v[128:129]
	v_mfma_f32_16x16x32_bf16 v[28:31], v[146:149], v[230:233], v[28:31]
	s_addc_u32 s47, s21, 0
	v_mfma_f32_16x16x32_bf16 v[20:23], v[154:157], v[230:233], v[20:23]
	s_add_i32 vcc_lo, vcc_lo, s25
	v_mfma_f32_16x16x32_bf16 v[12:15], v[146:149], v[238:241], v[12:15]
	global_load_lds_dwordx4 v[158:159], off
	v_mfma_f32_16x16x32_bf16 v[4:7], v[154:157], v[238:241], v[4:7]
	v_lshl_add_u64 v[196:197], s[46:47], 0, v[162:163]
	v_mfma_f32_16x16x32_bf16 v[60:63], v[150:153], v[218:221], v[60:63]
	s_mov_b32 m0, vcc_lo
	v_mfma_f32_16x16x32_bf16 v[52:55], v[174:177], v[218:221], v[52:55]
	v_lshl_add_u64 v[198:199], s[28:29], 0, v[130:131]
	v_mfma_f32_16x16x32_bf16 v[44:47], v[150:153], v[226:229], v[44:47]
	global_load_lds_dwordx4 v[196:197], off
	v_mfma_f32_16x16x32_bf16 v[36:39], v[174:177], v[226:229], v[36:39]
	v_lshl_add_u64 v[196:197], s[46:47], 0, v[128:129]
	v_mfma_f32_16x16x32_bf16 v[28:31], v[150:153], v[234:237], v[28:31]
	s_add_i32 m0, vcc_lo, 0x2000
	v_mfma_f32_16x16x32_bf16 v[20:23], v[174:177], v[234:237], v[20:23]
	global_load_lds_dwordx4 v[196:197], off
	v_mfma_f32_16x16x32_bf16 v[12:15], v[150:153], v[242:245], v[12:15]
	v_lshl_add_u64 v[196:197], s[28:29], 0, v[132:133]
	v_mfma_f32_16x16x32_bf16 v[4:7], v[174:177], v[242:245], v[4:7]
	s_mov_b32 m0, s30
	s_setprio 0
	s_setprio 1
	v_mfma_f32_16x16x32_bf16 v[56:59], v[178:181], v[214:217], v[56:59]
	global_load_lds_dwordx4 v[196:197], off
	v_mfma_f32_16x16x32_bf16 v[48:51], v[186:189], v[214:217], v[48:51]
	s_mov_b32 m0, s31
	v_mfma_f32_16x16x32_bf16 v[40:43], v[178:181], v[222:225], v[40:43]
	global_load_lds_dwordx4 v[198:199], off
	v_mfma_f32_16x16x32_bf16 v[32:35], v[186:189], v[222:225], v[32:35]
	v_mfma_f32_16x16x32_bf16 v[24:27], v[178:181], v[230:233], v[24:27]
	v_mfma_f32_16x16x32_bf16 v[16:19], v[186:189], v[230:233], v[16:19]
	v_mfma_f32_16x16x32_bf16 v[8:11], v[178:181], v[238:241], v[8:11]
	v_mfma_f32_16x16x32_bf16 v[0:3], v[186:189], v[238:241], v[0:3]
	s_barrier
; #define PG8_STAGE(bufoff, gbase, voff) do { _Pragma("unroll") for (int _i = 0; _i < 2; ++_i) \
;         __builtin_amdgcn_global_load_lds((const unsigned*)((const char*)(gbase) + (voff)[_i]), (PG8_LAS unsigned*)(lds + (bufoff) + ldsw + _i * 8192), 16, 0, 0); } while (0)
; #define PG8_LDA(dst, b, h) do { _Pragma("unroll") for (int m = 0; m < 4; ++m) _Pragma("unroll") for (int k = 0; k < 2; ++k) dst[m][k] = *(const PG8_LAS bf16x8*)(lds + PG8_SA(b, h) + aoff + m * 2048 + k * 1024); } while (0)
; #define PG8_LDB(dst, b, h) do { _Pragma("unroll") for (int n = 0; n < 2; ++n) _Pragma("unroll") for (int k = 0; k < 2; ++k) dst[n][k] = *(const PG8_LAS bf16x8*)(lds + PG8_SB(b, h) + boff + n * 2048 + k * 1024); } while (0)
; #define PG8_MMA(ai, bj, At, Bt) do { __builtin_amdgcn_s_setprio(1); _Pragma("unroll") for (int m = 0; m < 4; ++m) _Pragma("unroll") for (int n = 0; n < 2; ++n) _Pragma("unroll") for (int k = 0; k < 2; ++k) \
;         acc[ai][bj][m][n] = __builtin_amdgcn_mfma_f32_16x16x32_bf16(Bt[n][k], At[m][k], acc[ai][bj][m][n], 0, 0, 0); __builtin_amdgcn_s_setprio(0); } while (0)
; #define PG8_WAIT_V(n) asm volatile("s_waitcnt vmcnt(" #n ")" ::: "memory")
; #define PG8_WAIT_L(n) asm volatile("s_waitcnt lgkmcnt(" #n ")" ::: "memory")
; #define PG8_BAR __builtin_amdgcn_s_barrier()
; #define PG8_SCHED __builtin_amdgcn_sched_barrier(0)
; template <class Epi, class Sched, bool ALIGN_EPI = false, bool SP2 = false>
; __device__ __forceinline__ void gemm_phase(PG8_LAS unsigned char* lds, const Gemm g, const Sched& S, const Epi& E) {
;     ...
;             PG8_WAIT_V(8); PG8_WAIT_L(0); PG8_BAR; PG8_MMA(1, 0, At, B0); PG8_MMA(1, 1, At, B1); PG8_BAR; PG8_SCHED;
;             PG8_LDB(B0, 1, 0); PG8_LDB(B1, 1, 1); PG8_SCHED; PG8_LDA(At, 1, 0); PG8_STAGE(PG8_SA(0, 1), a2 + hstep, voffA);
;             PG8_WAIT_V(8); PG8_WAIT_L(0); PG8_BAR; PG8_MMA(0, 0, At, B0); PG8_MMA(0, 1, At, B1); PG8_BAR; PG8_SCHED;
	s_setprio 2
	v_mfma_f32_16x16x32_bf16 v[56:59], v[182:185], v[218:221], v[56:59]
	v_mfma_f32_16x16x32_bf16 v[48:51], v[210:213], v[218:221], v[48:51]
	v_mfma_f32_16x16x32_bf16 v[40:43], v[182:185], v[226:229], v[40:43]
	v_mfma_f32_16x16x32_bf16 v[32:35], v[210:213], v[226:229], v[32:35]
	v_mfma_f32_16x16x32_bf16 v[24:27], v[182:185], v[234:237], v[24:27]
	v_mfma_f32_16x16x32_bf16 v[16:19], v[210:213], v[234:237], v[16:19]
	v_mfma_f32_16x16x32_bf16 v[8:11], v[182:185], v[242:245], v[8:11]
	v_mfma_f32_16x16x32_bf16 v[0:3], v[210:213], v[242:245], v[0:3]
	s_setprio 0
	s_add_i32 s46, 0, 0x18000
	v_add_u32_e32 v145, s46, v141
	s_add_i32 s47, 0, 0x1c000
	ds_read_b128 v[146:149], v145
	ds_read_b128 v[150:153], v145 offset:1024
	ds_read_b128 v[154:157], v145 offset:2048
	ds_read_b128 v[174:177], v145 offset:3072
	v_add_u32_e32 v145, s47, v141
	ds_read_b128 v[178:181], v145
	ds_read_b128 v[182:185], v145 offset:1024
	ds_read_b128 v[186:189], v145 offset:2048
	ds_read_b128 v[210:213], v145 offset:3072
	s_add_u32 s28, s28, 0x80000
	s_addc_u32 s29, s29, 0
	s_mov_b32 m0, s70
	v_lshl_add_u64 v[246:247], s[28:29], 0, v[132:133]
	ds_read_b128 v[214:217], v144 offset:32768
	ds_read_b128 v[218:221], v144 offset:33792
	ds_read_b128 v[222:225], v144 offset:34816
	ds_read_b128 v[226:229], v144 offset:35840
	ds_read_b128 v[230:233], v144 offset:36864
	ds_read_b128 v[234:237], v144 offset:37888
	ds_read_b128 v[238:241], v144 offset:38912
	ds_read_b128 v[242:245], v144 offset:39936
	s_waitcnt vmcnt(6)
	s_nop 0
	s_barrier
	s_setprio 1
	s_waitcnt lgkmcnt(0)
	v_mfma_f32_16x16x32_bf16 v[124:127], v[146:149], v[214:217], v[124:127]
	global_load_lds_dwordx4 v[246:247], off
	v_mfma_f32_16x16x32_bf16 v[116:119], v[154:157], v[214:217], v[116:119]
	v_lshl_add_u64 v[246:247], s[28:29], 0, v[130:131]
	v_mfma_f32_16x16x32_bf16 v[108:111], v[146:149], v[222:225], v[108:111]
	s_mov_b32 m0, s71
	v_mfma_f32_16x16x32_bf16 v[100:103], v[154:157], v[222:225], v[100:103]
	global_load_lds_dwordx4 v[246:247], off
	v_mfma_f32_16x16x32_bf16 v[92:95], v[146:149], v[230:233], v[92:95]
	v_mfma_f32_16x16x32_bf16 v[84:87], v[154:157], v[230:233], v[84:87]
	v_mfma_f32_16x16x32_bf16 v[76:79], v[146:149], v[238:241], v[76:79]
	v_mfma_f32_16x16x32_bf16 v[68:71], v[154:157], v[238:241], v[68:71]
	v_mfma_f32_16x16x32_bf16 v[124:127], v[150:153], v[218:221], v[124:127]
	v_mfma_f32_16x16x32_bf16 v[116:119], v[174:177], v[218:221], v[116:119]
	v_mfma_f32_16x16x32_bf16 v[108:111], v[150:153], v[226:229], v[108:111]
	v_mfma_f32_16x16x32_bf16 v[100:103], v[174:177], v[226:229], v[100:103]
	v_mfma_f32_16x16x32_bf16 v[92:95], v[150:153], v[234:237], v[92:95]
	v_mfma_f32_16x16x32_bf16 v[84:87], v[174:177], v[234:237], v[84:87]
	v_mfma_f32_16x16x32_bf16 v[76:79], v[150:153], v[242:245], v[76:79]
	v_mfma_f32_16x16x32_bf16 v[68:71], v[174:177], v[242:245], v[68:71]
	s_setprio 0
	s_setprio 1
	v_mfma_f32_16x16x32_bf16 v[120:123], v[178:181], v[214:217], v[120:123]
	v_mfma_f32_16x16x32_bf16 v[112:115], v[186:189], v[214:217], v[112:115]
	v_mfma_f32_16x16x32_bf16 v[104:107], v[178:181], v[222:225], v[104:107]
	v_mfma_f32_16x16x32_bf16 v[96:99], v[186:189], v[222:225], v[96:99]
	v_mfma_f32_16x16x32_bf16 v[88:91], v[178:181], v[230:233], v[88:91]
	v_mfma_f32_16x16x32_bf16 v[80:83], v[186:189], v[230:233], v[80:83]
	v_mfma_f32_16x16x32_bf16 v[72:75], v[178:181], v[238:241], v[72:75]
	v_mfma_f32_16x16x32_bf16 v[64:67], v[186:189], v[238:241], v[64:67]
	s_barrier
; #define PG8_STAGE(bufoff, gbase, voff) do { _Pragma("unroll") for (int _i = 0; _i < 2; ++_i) \
;         __builtin_amdgcn_global_load_lds((const unsigned*)((const char*)(gbase) + (voff)[_i]), (PG8_LAS unsigned*)(lds + (bufoff) + ldsw + _i * 8192), 16, 0, 0); } while (0)
; #define PG8_LDA(dst, b, h) do { _Pragma("unroll") for (int m = 0; m < 4; ++m) _Pragma("unroll") for (int k = 0; k < 2; ++k) dst[m][k] = *(const PG8_LAS bf16x8*)(lds + PG8_SA(b, h) + aoff + m * 2048 + k * 1024); } while (0)
; #define PG8_MMA(ai, bj, At, Bt) do { __builtin_amdgcn_s_setprio(1); _Pragma("unroll") for (int m = 0; m < 4; ++m) _Pragma("unroll") for (int n = 0; n < 2; ++n) _Pragma("unroll") for (int k = 0; k < 2; ++k) \
;         acc[ai][bj][m][n] = __builtin_amdgcn_mfma_f32_16x16x32_bf16(Bt[n][k], At[m][k], acc[ai][bj][m][n], 0, 0, 0); __builtin_amdgcn_s_setprio(0); } while (0)
; #define PG8_WAIT_V(n) asm volatile("s_waitcnt vmcnt(" #n ")" ::: "memory")
; #define PG8_WAIT_L(n) asm volatile("s_waitcnt lgkmcnt(" #n ")" ::: "memory")
; #define PG8_BAR __builtin_amdgcn_s_barrier()
; #define PG8_SCHED __builtin_amdgcn_sched_barrier(0)
; template <class Epi, class Sched, bool ALIGN_EPI = false, bool SP2 = false>
; __device__ __forceinline__ void gemm_phase(PG8_LAS unsigned char* lds, const Gemm g, const Sched& S, const Epi& E) {
;     ...
;             PG8_WAIT_V(8); PG8_WAIT_L(0); PG8_BAR; PG8_MMA(0, 0, At, B0); PG8_MMA(0, 1, At, B1); PG8_BAR; PG8_SCHED;
;             PG8_LDA(At, 1, 1); PG8_STAGE(PG8_SB(1, 0), b3, voffB); PG8_STAGE(PG8_SB(1, 1), b3 + hstep, voffB); PG8_STAGE(PG8_SA(1, 0), a3, voffA);
;             PG8_WAIT_V(8); PG8_WAIT_L(0); PG8_BAR; PG8_MMA(1, 0, At, B0); PG8_MMA(1, 1, At, B1); PG8_BAR; PG8_SCHED;
	s_setprio 2
	v_mfma_f32_16x16x32_bf16 v[120:123], v[182:185], v[218:221], v[120:123]
	v_mfma_f32_16x16x32_bf16 v[112:115], v[210:213], v[218:221], v[112:115]
	v_mfma_f32_16x16x32_bf16 v[104:107], v[182:185], v[226:229], v[104:107]
	v_mfma_f32_16x16x32_bf16 v[96:99], v[210:213], v[226:229], v[96:99]
	v_mfma_f32_16x16x32_bf16 v[88:91], v[182:185], v[234:237], v[88:91]
	v_mfma_f32_16x16x32_bf16 v[80:83], v[210:213], v[234:237], v[80:83]
	v_mfma_f32_16x16x32_bf16 v[72:75], v[182:185], v[242:245], v[72:75]
	v_mfma_f32_16x16x32_bf16 v[64:67], v[210:213], v[242:245], v[64:67]
	s_setprio 0
	s_add_i32 s28, s46, s25
	v_lshl_add_u64 v[138:139], v[138:139], 0, s[58:59]
	s_mov_b32 m0, s28
	ds_read_b128 v[214:217], v144 offset:49152
	ds_read_b128 v[218:221], v144 offset:50176
	ds_read_b128 v[222:225], v144 offset:51200
	ds_read_b128 v[226:229], v144 offset:52224
	ds_read_b128 v[230:233], v144 offset:53248
	ds_read_b128 v[234:237], v144 offset:54272
	ds_read_b128 v[238:241], v144 offset:55296
	ds_read_b128 v[242:245], v144 offset:56320
	s_waitcnt vmcnt(2)
	s_nop 0
	s_barrier
	s_setprio 1
	s_waitcnt lgkmcnt(0)
	v_mfma_f32_16x16x32_bf16 v[60:63], v[146:149], v[214:217], v[60:63]
	global_load_lds_dwordx4 v[138:139], off
	v_mfma_f32_16x16x32_bf16 v[52:55], v[154:157], v[214:217], v[52:55]
	s_add_i32 m0, s28, 0x2000
	v_mfma_f32_16x16x32_bf16 v[44:47], v[146:149], v[222:225], v[44:47]
	s_add_u32 s20, s20, 0x80080
	v_mfma_f32_16x16x32_bf16 v[36:39], v[154:157], v[222:225], v[36:39]
	v_lshl_add_u64 v[138:139], v[158:159], 0, s[58:59]
	v_mfma_f32_16x16x32_bf16 v[28:31], v[146:149], v[230:233], v[28:31]
	s_addc_u32 s21, s21, 0
	v_mfma_f32_16x16x32_bf16 v[20:23], v[154:157], v[230:233], v[20:23]
	s_add_i32 s28, s47, s25
	v_mfma_f32_16x16x32_bf16 v[12:15], v[146:149], v[238:241], v[12:15]
	global_load_lds_dwordx4 v[138:139], off
	v_mfma_f32_16x16x32_bf16 v[4:7], v[154:157], v[238:241], v[4:7]
	v_lshl_add_u64 v[138:139], s[20:21], 0, v[162:163]
	v_mfma_f32_16x16x32_bf16 v[60:63], v[150:153], v[218:221], v[60:63]
	s_mov_b32 m0, s28
	v_mfma_f32_16x16x32_bf16 v[52:55], v[174:177], v[218:221], v[52:55]
	global_load_lds_dwordx4 v[138:139], off
	v_mfma_f32_16x16x32_bf16 v[44:47], v[150:153], v[226:229], v[44:47]
	v_lshl_add_u64 v[138:139], s[20:21], 0, v[128:129]
	v_mfma_f32_16x16x32_bf16 v[36:39], v[174:177], v[226:229], v[36:39]
	s_add_i32 m0, s28, 0x2000
	v_mfma_f32_16x16x32_bf16 v[28:31], v[150:153], v[234:237], v[28:31]
	global_load_lds_dwordx4 v[138:139], off
	v_mfma_f32_16x16x32_bf16 v[20:23], v[174:177], v[234:237], v[20:23]
	v_lshl_add_u64 v[138:139], v[196:197], 0, s[58:59]
	v_mfma_f32_16x16x32_bf16 v[12:15], v[150:153], v[242:245], v[12:15]
	s_mov_b32 m0, s72
	v_mfma_f32_16x16x32_bf16 v[4:7], v[174:177], v[242:245], v[4:7]
	global_load_lds_dwordx4 v[138:139], off
	s_setprio 0
	s_setprio 1
	v_mfma_f32_16x16x32_bf16 v[56:59], v[178:181], v[214:217], v[56:59]
	v_lshl_add_u64 v[138:139], v[198:199], 0, s[58:59]
	v_mfma_f32_16x16x32_bf16 v[48:51], v[186:189], v[214:217], v[48:51]
	s_mov_b32 m0, s73
	v_mfma_f32_16x16x32_bf16 v[40:43], v[178:181], v[222:225], v[40:43]
	global_load_lds_dwordx4 v[138:139], off
	v_mfma_f32_16x16x32_bf16 v[32:35], v[186:189], v[222:225], v[32:35]
	v_mfma_f32_16x16x32_bf16 v[24:27], v[178:181], v[230:233], v[24:27]
	v_mfma_f32_16x16x32_bf16 v[16:19], v[186:189], v[230:233], v[16:19]
	v_mfma_f32_16x16x32_bf16 v[8:11], v[178:181], v[238:241], v[8:11]
	v_mfma_f32_16x16x32_bf16 v[0:3], v[186:189], v[238:241], v[0:3]
	s_barrier
	s_setprio 2
	v_mfma_f32_16x16x32_bf16 v[56:59], v[182:185], v[218:221], v[56:59]
	v_mfma_f32_16x16x32_bf16 v[48:51], v[210:213], v[218:221], v[48:51]
	v_mfma_f32_16x16x32_bf16 v[40:43], v[182:185], v[226:229], v[40:43]
	v_mfma_f32_16x16x32_bf16 v[32:35], v[210:213], v[226:229], v[32:35]
	v_mfma_f32_16x16x32_bf16 v[24:27], v[182:185], v[234:237], v[24:27]
	v_mfma_f32_16x16x32_bf16 v[16:19], v[210:213], v[234:237], v[16:19]
	v_mfma_f32_16x16x32_bf16 v[8:11], v[182:185], v[242:245], v[8:11]
	v_mfma_f32_16x16x32_bf16 v[0:3], v[210:213], v[242:245], v[0:3]
	s_setprio 0
	s_add_i32 s95, s95, 2
	s_add_u32 s87, s87, 0x100
	s_addc_u32 s94, s94, 0
	s_add_u32 s92, s92, 0x100
	s_addc_u32 s93, s93, 0
	s_cmp_gt_u32 s95, 29
	s_cbranch_scc0 .LBB0_368
	s_and_b64 vcc, exec, s[82:83]
	s_cbranch_vccz .LBB0_371
	s_barrier

; #define PG8_STAGE(bufoff, gbase, voff) do { _Pragma("unroll") for (int _i = 0; _i < 2; ++_i) \
;         __builtin_amdgcn_global_load_lds((const unsigned*)((const char*)(gbase) + (voff)[_i]), (PG8_LAS unsigned*)(lds + (bufoff) + ldsw + _i * 8192), 16, 0, 0); } while (0)
; #define PG8_LDA(dst, b, h) do { _Pragma("unroll") for (int m = 0; m < 4; ++m) _Pragma("unroll") for (int k = 0; k < 2; ++k) dst[m][k] = *(const PG8_LAS bf16x8*)(lds + PG8_SA(b, h) + aoff + m * 2048 + k * 1024); } while (0)
; #define PG8_LDB(dst, b, h) do { _Pragma("unroll") for (int n = 0; n < 2; ++n) _Pragma("unroll") for (int k = 0; k < 2; ++k) dst[n][k] = *(const PG8_LAS bf16x8*)(lds + PG8_SB(b, h) + boff + n * 2048 + k * 1024); } while (0)
; #define PG8_MMA(ai, bj, At, Bt) do { __builtin_amdgcn_s_setprio(1); _Pragma("unroll") for (int m = 0; m < 4; ++m) _Pragma("unroll") for (int n = 0; n < 2; ++n) _Pragma("unroll") for (int k = 0; k < 2; ++k) \
;         acc[ai][bj][m][n] = __builtin_amdgcn_mfma_f32_16x16x32_bf16(Bt[n][k], At[m][k], acc[ai][bj][m][n], 0, 0, 0); __builtin_amdgcn_s_setprio(0); } while (0)
; #define PG8_WAIT_V(n) asm volatile("s_waitcnt vmcnt(" #n ")" ::: "memory")
; #define PG8_WAIT_L(n) asm volatile("s_waitcnt lgkmcnt(" #n ")" ::: "memory")
; #define PG8_BAR __builtin_amdgcn_s_barrier()
; #define PG8_SCHED __builtin_amdgcn_sched_barrier(0)
; template <class Epi, class Sched, bool ALIGN_EPI = false, bool SP2 = false>
; __device__ __forceinline__ void gemm_phase(PG8_LAS unsigned char* lds, const Gemm g, const Sched& S, const Epi& E) {
;     ...
;             const char* a2 = last ? nA : cA + (size_t)(t + 2) * kstep; const char* b2 = last ? nB : cB + (size_t)(t + 2) * kstep;
;             const char* a3 = a2 + kstep; const char* b3 = b2 + kstep;
;             if (last && has_next) S.a_ready(nxt);
;             if constexpr (SP2) {
;             PG8_LDB(B0, 0, 0); PG8_LDB(B1, 0, 1); PG8_SCHED; PG8_LDA(At, 0, 0); PG8_STAGE(PG8_SA(1, 1), a1 + hstep, voffA);
;             PG8_WAIT_V(8); PG8_WAIT_L(0); PG8_BAR; PG8_MMA(0, 0, At, B0); PG8_MMA(0, 1, At, B1); PG8_BAR; PG8_SCHED;
;             PG8_LDA(At, 0, 1); PG8_STAGE(PG8_SB(0, 0), b2, voffB); PG8_STAGE(PG8_SB(0, 1), b2 + hstep, voffB); PG8_STAGE(PG8_SA(0, 0), a2, voffA);
;             PG8_WAIT_V(8); PG8_WAIT_L(0); PG8_BAR; PG8_MMA(1, 0, At, B0); PG8_MMA(1, 1, At, B1); PG8_BAR; PG8_SCHED;
.LBB0_406:
	s_add_u32 s94, s92, 0x100
	s_addc_u32 s95, s93, 0
	s_add_i32 s46, 0, 0x10000
	s_cmpk_eq_i32 s81, 0x54
	s_cselect_b32 s29, s45, s95
	s_cselect_b32 s28, s44, s94
	s_cselect_b32 s21, s89, s79
	s_cselect_b32 s20, s88, s78
	s_add_i32 s91, 0, 0x14000
	v_add_u32_e32 v140, s46, v211
	v_add_u32_e32 v182, s91, v211
	ds_read_b128 v[128:131], v140
	ds_read_b128 v[132:135], v140 offset:1024
	ds_read_b128 v[136:139], v140 offset:2048
	ds_read_b128 v[140:143], v140 offset:3072
	ds_read_b128 v[144:147], v182
	ds_read_b128 v[148:151], v182 offset:1024
	ds_read_b128 v[178:181], v182 offset:2048
	ds_read_b128 v[182:185], v182 offset:3072
	v_lshl_add_u64 v[196:197], s[92:93], 0, v[174:175]
	s_add_i32 m0, s30, 0xc000
	ds_read_b128 v[186:189], v213
	ds_read_b128 v[214:217], v213 offset:1024
	ds_read_b128 v[218:221], v213 offset:2048
	ds_read_b128 v[222:225], v213 offset:3072
	ds_read_b128 v[226:229], v213 offset:4096
	ds_read_b128 v[230:233], v213 offset:5120
	ds_read_b128 v[234:237], v213 offset:6144
	ds_read_b128 v[238:241], v213 offset:7168
	s_waitcnt vmcnt(6)
	s_nop 0
	s_barrier
	s_setprio 1
	s_waitcnt lgkmcnt(0)
	v_mfma_f32_16x16x32_bf16 v[124:127], v[128:131], v[186:189], v[124:127]
	global_load_lds_dwordx4 v[196:197], off
	v_mfma_f32_16x16x32_bf16 v[120:123], v[136:139], v[186:189], v[120:123]
	v_lshl_add_u64 v[196:197], s[92:93], 0, v[176:177]
	v_mfma_f32_16x16x32_bf16 v[108:111], v[128:131], v[218:221], v[108:111]
	s_add_i32 m0, s30, 0xe000
	v_mfma_f32_16x16x32_bf16 v[104:107], v[136:139], v[218:221], v[104:107]
	global_load_lds_dwordx4 v[196:197], off
	v_mfma_f32_16x16x32_bf16 v[92:95], v[128:131], v[226:229], v[92:95]
	v_mfma_f32_16x16x32_bf16 v[88:91], v[136:139], v[226:229], v[88:91]
	v_mfma_f32_16x16x32_bf16 v[76:79], v[128:131], v[234:237], v[76:79]
	v_mfma_f32_16x16x32_bf16 v[72:75], v[136:139], v[234:237], v[72:75]
	v_mfma_f32_16x16x32_bf16 v[124:127], v[132:135], v[214:217], v[124:127]
	v_mfma_f32_16x16x32_bf16 v[120:123], v[140:143], v[214:217], v[120:123]
	v_mfma_f32_16x16x32_bf16 v[108:111], v[132:135], v[222:225], v[108:111]
	v_mfma_f32_16x16x32_bf16 v[104:107], v[140:143], v[222:225], v[104:107]
	v_mfma_f32_16x16x32_bf16 v[92:95], v[132:135], v[230:233], v[92:95]
	v_mfma_f32_16x16x32_bf16 v[88:91], v[140:143], v[230:233], v[88:91]
	v_mfma_f32_16x16x32_bf16 v[76:79], v[132:135], v[238:241], v[76:79]
	v_mfma_f32_16x16x32_bf16 v[72:75], v[140:143], v[238:241], v[72:75]
	s_setprio 0
	s_setprio 1
	v_mfma_f32_16x16x32_bf16 v[116:119], v[144:147], v[186:189], v[116:119]
	v_mfma_f32_16x16x32_bf16 v[112:115], v[178:181], v[186:189], v[112:115]
	v_mfma_f32_16x16x32_bf16 v[100:103], v[144:147], v[218:221], v[100:103]
	v_mfma_f32_16x16x32_bf16 v[96:99], v[178:181], v[218:221], v[96:99]
	v_mfma_f32_16x16x32_bf16 v[84:87], v[144:147], v[226:229], v[84:87]
	v_mfma_f32_16x16x32_bf16 v[80:83], v[178:181], v[226:229], v[80:83]
	v_mfma_f32_16x16x32_bf16 v[68:71], v[144:147], v[234:237], v[68:71]
	v_mfma_f32_16x16x32_bf16 v[64:67], v[178:181], v[234:237], v[64:67]
	s_barrier
	s_setprio 2
	v_mfma_f32_16x16x32_bf16 v[116:119], v[148:151], v[214:217], v[116:119]
	v_mfma_f32_16x16x32_bf16 v[112:115], v[182:185], v[214:217], v[112:115]
	v_mfma_f32_16x16x32_bf16 v[100:103], v[148:151], v[222:225], v[100:103]
	v_mfma_f32_16x16x32_bf16 v[96:99], v[182:185], v[222:225], v[96:99]
	v_mfma_f32_16x16x32_bf16 v[84:87], v[148:151], v[230:233], v[84:87]
	v_mfma_f32_16x16x32_bf16 v[80:83], v[182:185], v[230:233], v[80:83]
	v_mfma_f32_16x16x32_bf16 v[68:71], v[148:151], v[238:241], v[68:71]
	v_mfma_f32_16x16x32_bf16 v[64:67], v[182:185], v[238:241], v[64:67]
	s_setprio 0
	s_add_i32 s46, s46, s25
	v_lshl_add_u64 v[196:197], s[20:21], 0, v[162:163]
	s_mov_b32 m0, s46
	ds_read_b128 v[186:189], v213 offset:16384
	ds_read_b128 v[214:217], v213 offset:17408
	ds_read_b128 v[218:221], v213 offset:18432
	ds_read_b128 v[222:225], v213 offset:19456
	ds_read_b128 v[226:229], v213 offset:20480
	ds_read_b128 v[230:233], v213 offset:21504
	ds_read_b128 v[234:237], v213 offset:22528
	ds_read_b128 v[238:241], v213 offset:23552
	s_waitcnt vmcnt(2)
	s_nop 0
	s_barrier
	s_setprio 1
	s_waitcnt lgkmcnt(0)
	v_mfma_f32_16x16x32_bf16 v[60:63], v[128:131], v[186:189], v[60:63]
	global_load_lds_dwordx4 v[196:197], off
	v_mfma_f32_16x16x32_bf16 v[56:59], v[136:139], v[186:189], v[56:59]
	s_add_i32 m0, s46, 0x2000
	v_mfma_f32_16x16x32_bf16 v[44:47], v[128:131], v[218:221], v[44:47]
	s_add_u32 s46, s20, 0x160000
	v_mfma_f32_16x16x32_bf16 v[40:43], v[136:139], v[218:221], v[40:43]
	v_lshl_add_u64 v[198:199], s[20:21], 0, v[152:153]
	v_mfma_f32_16x16x32_bf16 v[28:31], v[128:131], v[226:229], v[28:31]
	s_addc_u32 s47, s21, 0
	v_mfma_f32_16x16x32_bf16 v[24:27], v[136:139], v[226:229], v[24:27]
	s_add_i32 s91, s91, s25
	v_mfma_f32_16x16x32_bf16 v[12:15], v[128:131], v[234:237], v[12:15]
	global_load_lds_dwordx4 v[198:199], off
	v_mfma_f32_16x16x32_bf16 v[8:11], v[136:139], v[234:237], v[8:11]
	v_lshl_add_u64 v[242:243], s[46:47], 0, v[162:163]
	v_mfma_f32_16x16x32_bf16 v[60:63], v[132:135], v[214:217], v[60:63]
	s_mov_b32 m0, s91
	v_mfma_f32_16x16x32_bf16 v[56:59], v[140:143], v[214:217], v[56:59]
	v_lshl_add_u64 v[244:245], s[28:29], 0, v[154:155]
	v_mfma_f32_16x16x32_bf16 v[44:47], v[132:135], v[222:225], v[44:47]
	global_load_lds_dwordx4 v[242:243], off
	v_mfma_f32_16x16x32_bf16 v[40:43], v[140:143], v[222:225], v[40:43]
	v_lshl_add_u64 v[242:243], s[46:47], 0, v[152:153]
	v_mfma_f32_16x16x32_bf16 v[28:31], v[132:135], v[230:233], v[28:31]
	s_add_i32 m0, s91, 0x2000
	v_mfma_f32_16x16x32_bf16 v[24:27], v[140:143], v[230:233], v[24:27]
	global_load_lds_dwordx4 v[242:243], off
	v_mfma_f32_16x16x32_bf16 v[12:15], v[132:135], v[238:241], v[12:15]
	v_lshl_add_u64 v[242:243], s[28:29], 0, v[156:157]
	v_mfma_f32_16x16x32_bf16 v[8:11], v[140:143], v[238:241], v[8:11]
	s_mov_b32 m0, s30
	s_setprio 0
	s_setprio 1
	v_mfma_f32_16x16x32_bf16 v[52:55], v[144:147], v[186:189], v[52:55]
	global_load_lds_dwordx4 v[242:243], off
	v_mfma_f32_16x16x32_bf16 v[48:51], v[178:181], v[186:189], v[48:51]
	s_mov_b32 m0, s31
	v_mfma_f32_16x16x32_bf16 v[36:39], v[144:147], v[218:221], v[36:39]
	global_load_lds_dwordx4 v[244:245], off
	v_mfma_f32_16x16x32_bf16 v[32:35], v[178:181], v[218:221], v[32:35]
	v_mfma_f32_16x16x32_bf16 v[20:23], v[144:147], v[226:229], v[20:23]
	v_mfma_f32_16x16x32_bf16 v[16:19], v[178:181], v[226:229], v[16:19]
	v_mfma_f32_16x16x32_bf16 v[4:7], v[144:147], v[234:237], v[4:7]
	v_mfma_f32_16x16x32_bf16 v[0:3], v[178:181], v[234:237], v[0:3]
	s_barrier
; #define PG8_STAGE(bufoff, gbase, voff) do { _Pragma("unroll") for (int _i = 0; _i < 2; ++_i) \
;         __builtin_amdgcn_global_load_lds((const unsigned*)((const char*)(gbase) + (voff)[_i]), (PG8_LAS unsigned*)(lds + (bufoff) + ldsw + _i * 8192), 16, 0, 0); } while (0)
; #define PG8_LDA(dst, b, h) do { _Pragma("unroll") for (int m = 0; m < 4; ++m) _Pragma("unroll") for (int k = 0; k < 2; ++k) dst[m][k] = *(const PG8_LAS bf16x8*)(lds + PG8_SA(b, h) + aoff + m * 2048 + k * 1024); } while (0)
; #define PG8_LDB(dst, b, h) do { _Pragma("unroll") for (int n = 0; n < 2; ++n) _Pragma("unroll") for (int k = 0; k < 2; ++k) dst[n][k] = *(const PG8_LAS bf16x8*)(lds + PG8_SB(b, h) + boff + n * 2048 + k * 1024); } while (0)
; #define PG8_MMA(ai, bj, At, Bt) do { __builtin_amdgcn_s_setprio(1); _Pragma("unroll") for (int m = 0; m < 4; ++m) _Pragma("unroll") for (int n = 0; n < 2; ++n) _Pragma("unroll") for (int k = 0; k < 2; ++k) \
;         acc[ai][bj][m][n] = __builtin_amdgcn_mfma_f32_16x16x32_bf16(Bt[n][k], At[m][k], acc[ai][bj][m][n], 0, 0, 0); __builtin_amdgcn_s_setprio(0); } while (0)
; #define PG8_WAIT_V(n) asm volatile("s_waitcnt vmcnt(" #n ")" ::: "memory")
; #define PG8_WAIT_L(n) asm volatile("s_waitcnt lgkmcnt(" #n ")" ::: "memory")
; #define PG8_BAR __builtin_amdgcn_s_barrier()
; #define PG8_SCHED __builtin_amdgcn_sched_barrier(0)
; template <class Epi, class Sched, bool ALIGN_EPI = false, bool SP2 = false>
; __device__ __forceinline__ void gemm_phase(PG8_LAS unsigned char* lds, const Gemm g, const Sched& S, const Epi& E) {
;     ...
;             PG8_WAIT_V(8); PG8_WAIT_L(0); PG8_BAR; PG8_MMA(1, 0, At, B0); PG8_MMA(1, 1, At, B1); PG8_BAR; PG8_SCHED;
;             PG8_LDB(B0, 1, 0); PG8_LDB(B1, 1, 1); PG8_SCHED; PG8_LDA(At, 1, 0); PG8_STAGE(PG8_SA(0, 1), a2 + hstep, voffA);
;             PG8_WAIT_V(8); PG8_WAIT_L(0); PG8_BAR; PG8_MMA(0, 0, At, B0); PG8_MMA(0, 1, At, B1); PG8_BAR; PG8_SCHED;
	s_setprio 2
	v_mfma_f32_16x16x32_bf16 v[52:55], v[148:151], v[214:217], v[52:55]
	v_mfma_f32_16x16x32_bf16 v[48:51], v[182:185], v[214:217], v[48:51]
	v_mfma_f32_16x16x32_bf16 v[36:39], v[148:151], v[222:225], v[36:39]
	v_mfma_f32_16x16x32_bf16 v[32:35], v[182:185], v[222:225], v[32:35]
	v_mfma_f32_16x16x32_bf16 v[20:23], v[148:151], v[230:233], v[20:23]
	v_mfma_f32_16x16x32_bf16 v[16:19], v[182:185], v[230:233], v[16:19]
	v_mfma_f32_16x16x32_bf16 v[4:7], v[148:151], v[238:241], v[4:7]
	v_mfma_f32_16x16x32_bf16 v[0:3], v[182:185], v[238:241], v[0:3]
	s_setprio 0
	s_add_i32 s46, 0, 0x18000
	s_add_i32 s47, 0, 0x1c000
	v_add_u32_e32 v140, s46, v211
	v_add_u32_e32 v182, s47, v211
	ds_read_b128 v[128:131], v140
	ds_read_b128 v[132:135], v140 offset:1024
	ds_read_b128 v[136:139], v140 offset:2048
	ds_read_b128 v[140:143], v140 offset:3072
	ds_read_b128 v[144:147], v182
	ds_read_b128 v[148:151], v182 offset:1024
	ds_read_b128 v[178:181], v182 offset:2048
	ds_read_b128 v[182:185], v182 offset:3072
	s_add_u32 s28, s28, 0x160000
	s_addc_u32 s29, s29, 0
	s_mov_b32 m0, s70
	v_lshl_add_u64 v[246:247], s[28:29], 0, v[156:157]
	ds_read_b128 v[186:189], v213 offset:32768
	ds_read_b128 v[214:217], v213 offset:33792
	ds_read_b128 v[218:221], v213 offset:34816
	ds_read_b128 v[222:225], v213 offset:35840
	ds_read_b128 v[226:229], v213 offset:36864
	ds_read_b128 v[230:233], v213 offset:37888
	ds_read_b128 v[234:237], v213 offset:38912
	ds_read_b128 v[238:241], v213 offset:39936
	s_waitcnt vmcnt(6)
	s_nop 0
	s_barrier
	s_setprio 1
	s_waitcnt lgkmcnt(0)
	v_mfma_f32_16x16x32_bf16 v[124:127], v[128:131], v[186:189], v[124:127]
	global_load_lds_dwordx4 v[246:247], off
	v_mfma_f32_16x16x32_bf16 v[120:123], v[136:139], v[186:189], v[120:123]
	v_lshl_add_u64 v[246:247], s[28:29], 0, v[154:155]
	v_mfma_f32_16x16x32_bf16 v[108:111], v[128:131], v[218:221], v[108:111]
	s_mov_b32 m0, s71
	v_mfma_f32_16x16x32_bf16 v[104:107], v[136:139], v[218:221], v[104:107]
	global_load_lds_dwordx4 v[246:247], off
	v_mfma_f32_16x16x32_bf16 v[92:95], v[128:131], v[226:229], v[92:95]
	v_mfma_f32_16x16x32_bf16 v[88:91], v[136:139], v[226:229], v[88:91]
	v_mfma_f32_16x16x32_bf16 v[76:79], v[128:131], v[234:237], v[76:79]
	v_mfma_f32_16x16x32_bf16 v[72:75], v[136:139], v[234:237], v[72:75]
	v_mfma_f32_16x16x32_bf16 v[124:127], v[132:135], v[214:217], v[124:127]
	v_mfma_f32_16x16x32_bf16 v[120:123], v[140:143], v[214:217], v[120:123]
	v_mfma_f32_16x16x32_bf16 v[108:111], v[132:135], v[222:225], v[108:111]
	v_mfma_f32_16x16x32_bf16 v[104:107], v[140:143], v[222:225], v[104:107]
	v_mfma_f32_16x16x32_bf16 v[92:95], v[132:135], v[230:233], v[92:95]
	v_mfma_f32_16x16x32_bf16 v[88:91], v[140:143], v[230:233], v[88:91]
	v_mfma_f32_16x16x32_bf16 v[76:79], v[132:135], v[238:241], v[76:79]
	v_mfma_f32_16x16x32_bf16 v[72:75], v[140:143], v[238:241], v[72:75]
	s_setprio 0
	s_setprio 1
	v_mfma_f32_16x16x32_bf16 v[116:119], v[144:147], v[186:189], v[116:119]
	v_mfma_f32_16x16x32_bf16 v[112:115], v[178:181], v[186:189], v[112:115]
	v_mfma_f32_16x16x32_bf16 v[100:103], v[144:147], v[218:221], v[100:103]
	v_mfma_f32_16x16x32_bf16 v[96:99], v[178:181], v[218:221], v[96:99]
	v_mfma_f32_16x16x32_bf16 v[84:87], v[144:147], v[226:229], v[84:87]
	v_mfma_f32_16x16x32_bf16 v[80:83], v[178:181], v[226:229], v[80:83]
	v_mfma_f32_16x16x32_bf16 v[68:71], v[144:147], v[234:237], v[68:71]
	v_mfma_f32_16x16x32_bf16 v[64:67], v[178:181], v[234:237], v[64:67]
	s_barrier
; #define PG8_STAGE(bufoff, gbase, voff) do { _Pragma("unroll") for (int _i = 0; _i < 2; ++_i) \
;         __builtin_amdgcn_global_load_lds((const unsigned*)((const char*)(gbase) + (voff)[_i]), (PG8_LAS unsigned*)(lds + (bufoff) + ldsw + _i * 8192), 16, 0, 0); } while (0)
; #define PG8_LDA(dst, b, h) do { _Pragma("unroll") for (int m = 0; m < 4; ++m) _Pragma("unroll") for (int k = 0; k < 2; ++k) dst[m][k] = *(const PG8_LAS bf16x8*)(lds + PG8_SA(b, h) + aoff + m * 2048 + k * 1024); } while (0)
; #define PG8_MMA(ai, bj, At, Bt) do { __builtin_amdgcn_s_setprio(1); _Pragma("unroll") for (int m = 0; m < 4; ++m) _Pragma("unroll") for (int n = 0; n < 2; ++n) _Pragma("unroll") for (int k = 0; k < 2; ++k) \
;         acc[ai][bj][m][n] = __builtin_amdgcn_mfma_f32_16x16x32_bf16(Bt[n][k], At[m][k], acc[ai][bj][m][n], 0, 0, 0); __builtin_amdgcn_s_setprio(0); } while (0)
; #define PG8_WAIT_V(n) asm volatile("s_waitcnt vmcnt(" #n ")" ::: "memory")
; #define PG8_WAIT_L(n) asm volatile("s_waitcnt lgkmcnt(" #n ")" ::: "memory")
; #define PG8_BAR __builtin_amdgcn_s_barrier()
; #define PG8_SCHED __builtin_amdgcn_sched_barrier(0)
; template <class Epi, class Sched, bool ALIGN_EPI = false, bool SP2 = false>
; __device__ __forceinline__ void gemm_phase(PG8_LAS unsigned char* lds, const Gemm g, const Sched& S, const Epi& E) {
;     ...
;             PG8_WAIT_V(8); PG8_WAIT_L(0); PG8_BAR; PG8_MMA(0, 0, At, B0); PG8_MMA(0, 1, At, B1); PG8_BAR; PG8_SCHED;
;             PG8_LDA(At, 1, 1); PG8_STAGE(PG8_SB(1, 0), b3, voffB); PG8_STAGE(PG8_SB(1, 1), b3 + hstep, voffB); PG8_STAGE(PG8_SA(1, 0), a3, voffA);
;             PG8_WAIT_V(8); PG8_WAIT_L(0); PG8_BAR; PG8_MMA(1, 0, At, B0); PG8_MMA(1, 1, At, B1); PG8_BAR; PG8_SCHED;
	s_setprio 2
	v_mfma_f32_16x16x32_bf16 v[116:119], v[148:151], v[214:217], v[116:119]
	v_mfma_f32_16x16x32_bf16 v[112:115], v[182:185], v[214:217], v[112:115]
	v_mfma_f32_16x16x32_bf16 v[100:103], v[148:151], v[222:225], v[100:103]
	v_mfma_f32_16x16x32_bf16 v[96:99], v[182:185], v[222:225], v[96:99]
	v_mfma_f32_16x16x32_bf16 v[84:87], v[148:151], v[230:233], v[84:87]
	v_mfma_f32_16x16x32_bf16 v[80:83], v[182:185], v[230:233], v[80:83]
	v_mfma_f32_16x16x32_bf16 v[68:71], v[148:151], v[238:241], v[68:71]
	v_mfma_f32_16x16x32_bf16 v[64:67], v[182:185], v[238:241], v[64:67]
	s_setprio 0
	s_add_i32 s28, s46, s25
	v_lshl_add_u64 v[196:197], v[196:197], 0, s[58:59]
	s_mov_b32 m0, s28
	ds_read_b128 v[186:189], v213 offset:49152
	ds_read_b128 v[214:217], v213 offset:50176
	ds_read_b128 v[218:221], v213 offset:51200
	ds_read_b128 v[222:225], v213 offset:52224
	ds_read_b128 v[226:229], v213 offset:53248
	ds_read_b128 v[230:233], v213 offset:54272
	ds_read_b128 v[234:237], v213 offset:55296
	ds_read_b128 v[238:241], v213 offset:56320
	s_waitcnt vmcnt(2)
	s_nop 0
	s_barrier
	s_setprio 1
	s_waitcnt lgkmcnt(0)
	v_mfma_f32_16x16x32_bf16 v[60:63], v[128:131], v[186:189], v[60:63]
	global_load_lds_dwordx4 v[196:197], off
	v_mfma_f32_16x16x32_bf16 v[56:59], v[136:139], v[186:189], v[56:59]
	s_add_i32 m0, s28, 0x2000
	v_mfma_f32_16x16x32_bf16 v[44:47], v[128:131], v[218:221], v[44:47]
	s_add_u32 s20, s20, 0x160080
	v_mfma_f32_16x16x32_bf16 v[40:43], v[136:139], v[218:221], v[40:43]
	v_lshl_add_u64 v[196:197], v[198:199], 0, s[58:59]
	v_mfma_f32_16x16x32_bf16 v[28:31], v[128:131], v[226:229], v[28:31]
	s_addc_u32 s21, s21, 0
	v_mfma_f32_16x16x32_bf16 v[24:27], v[136:139], v[226:229], v[24:27]
	s_add_i32 s28, s47, s25
	v_mfma_f32_16x16x32_bf16 v[12:15], v[128:131], v[234:237], v[12:15]
	global_load_lds_dwordx4 v[196:197], off
	v_mfma_f32_16x16x32_bf16 v[8:11], v[136:139], v[234:237], v[8:11]
	v_lshl_add_u64 v[196:197], s[20:21], 0, v[162:163]
	v_mfma_f32_16x16x32_bf16 v[60:63], v[132:135], v[214:217], v[60:63]
	s_mov_b32 m0, s28
	v_mfma_f32_16x16x32_bf16 v[56:59], v[140:143], v[214:217], v[56:59]
	global_load_lds_dwordx4 v[196:197], off
	v_mfma_f32_16x16x32_bf16 v[44:47], v[132:135], v[222:225], v[44:47]
	v_lshl_add_u64 v[196:197], s[20:21], 0, v[152:153]
	v_mfma_f32_16x16x32_bf16 v[40:43], v[140:143], v[222:225], v[40:43]
	s_add_i32 m0, s28, 0x2000
	v_mfma_f32_16x16x32_bf16 v[28:31], v[132:135], v[230:233], v[28:31]
	global_load_lds_dwordx4 v[196:197], off
	v_mfma_f32_16x16x32_bf16 v[24:27], v[140:143], v[230:233], v[24:27]
	v_lshl_add_u64 v[196:197], v[242:243], 0, s[58:59]
	v_mfma_f32_16x16x32_bf16 v[12:15], v[132:135], v[238:241], v[12:15]
	s_mov_b32 m0, s72
	v_mfma_f32_16x16x32_bf16 v[8:11], v[140:143], v[238:241], v[8:11]
	global_load_lds_dwordx4 v[196:197], off
	s_setprio 0
	s_setprio 1
	v_mfma_f32_16x16x32_bf16 v[52:55], v[144:147], v[186:189], v[52:55]
	v_lshl_add_u64 v[196:197], v[244:245], 0, s[58:59]
	v_mfma_f32_16x16x32_bf16 v[48:51], v[178:181], v[186:189], v[48:51]
	s_mov_b32 m0, s73
	v_mfma_f32_16x16x32_bf16 v[36:39], v[144:147], v[218:221], v[36:39]
	global_load_lds_dwordx4 v[196:197], off
	v_mfma_f32_16x16x32_bf16 v[32:35], v[178:181], v[218:221], v[32:35]
	v_mfma_f32_16x16x32_bf16 v[20:23], v[144:147], v[226:229], v[20:23]
	v_mfma_f32_16x16x32_bf16 v[16:19], v[178:181], v[226:229], v[16:19]
	v_mfma_f32_16x16x32_bf16 v[4:7], v[144:147], v[234:237], v[4:7]
	v_mfma_f32_16x16x32_bf16 v[0:3], v[178:181], v[234:237], v[0:3]
	s_barrier
	s_setprio 2
	v_mfma_f32_16x16x32_bf16 v[52:55], v[148:151], v[214:217], v[52:55]
	v_mfma_f32_16x16x32_bf16 v[48:51], v[182:185], v[214:217], v[48:51]
	v_mfma_f32_16x16x32_bf16 v[36:39], v[148:151], v[222:225], v[36:39]
	v_mfma_f32_16x16x32_bf16 v[32:35], v[182:185], v[222:225], v[32:35]
	v_mfma_f32_16x16x32_bf16 v[20:23], v[148:151], v[230:233], v[20:23]
	v_mfma_f32_16x16x32_bf16 v[16:19], v[182:185], v[230:233], v[16:19]
	v_mfma_f32_16x16x32_bf16 v[4:7], v[148:151], v[238:241], v[4:7]
	v_mfma_f32_16x16x32_bf16 v[0:3], v[182:185], v[238:241], v[0:3]
	s_setprio 0
	s_add_i32 s81, s81, 2
	s_add_u32 s78, s78, 0x100
	s_addc_u32 s79, s79, 0
	s_cmpk_gt_u32 s81, 0x55
	s_mov_b64 s[92:93], s[94:95]
	s_cbranch_scc0 .LBB0_406
	s_and_b64 vcc, exec, s[14:15]
	s_cbranch_vccz .LBB0_409
	s_barrier
